# first K-iteration after an epilogue: the two leading load-segment waits no longer drain the epilogue stores (P4-P7 GEMMs)
# speedup vs baseline: 1.0063x; 1.0063x over previous
; #define PG8_STAGE(bufoff, gbase, voff) do { _Pragma("unroll") for (int _i = 0; _i < 2; ++_i) \
;         __builtin_amdgcn_global_load_lds((const unsigned*)((const char*)(gbase) + (voff)[_i]), (PG8_LAS unsigned*)(lds + (bufoff) + ldsw + _i * 8192), 16, 0, 0); } while (0)
; #define PG8_WAIT_V(n) asm volatile("s_waitcnt vmcnt(" #n ")" ::: "memory")
; #define PG8_BAR __builtin_amdgcn_s_barrier()
;     ...
;     const unsigned ldsw = (unsigned)wid * 1024u;
;     const int aoff = lds_byte(wr * 64 + fr, fq * 8), boff = lds_byte(wc * 32 + fr, fq * 8);
;     ...
;         PG8_STAGE(PG8_SB(0, 0), cB, voffB); PG8_STAGE(PG8_SB(0, 1), cB + hstepB, voffB); PG8_STAGE(PG8_SA(0, 0), cA, voffA); PG8_STAGE(PG8_SA(0, 1), cA + hstepA, voffA);
;         if (wr == 1) PG8_BAR;
;         PG8_WAIT_V(2); PG8_BAR;
;         PG8_STAGE(PG8_SB(1, 0), cB + kstep, voffB); PG8_STAGE(PG8_SA(1, 0), cA + kstep, voffA); PG8_STAGE(PG8_SB(1, 1), cB + hstepB + kstep, voffB);
;         PG8_WAIT_V(6); PG8_BAR;
.LBB0_953:
	s_lshl_b32 s5, s5, 5
	s_and_b32 s71, s5, 0x60
	s_add_i32 m0, s66, 0x18000
	v_lshl_add_u64 v[6:7], v[6:7], 0, s[22:23]
	s_lshl_b32 s70, s35, 6
	s_lshl_b32 s35, s35, 13
	s_lshl_b32 s5, s71, 7
	s_waitcnt vmcnt(2)
	s_barrier
	global_load_lds_dwordx4 v[6:7], off
	v_lshl_add_u64 v[4:5], v[4:5], 0, s[22:23]
	s_add_i32 m0, s66, 0x1a000
	s_add_i32 s72, s66, 0x8000
	s_add_i32 s73, s66, 0xa000
	global_load_lds_dwordx4 v[4:5], off
	v_lshl_add_u64 v[0:1], v[0:1], 0, s[22:23]
	s_mov_b32 m0, s72
	s_add_u32 s38, s28, 0x20080
	global_load_lds_dwordx4 v[0:1], off
	v_lshl_add_u64 v[0:1], v[2:3], 0, s[22:23]
	s_mov_b32 m0, s73
	s_addc_u32 s39, s29, 0
	global_load_lds_dwordx4 v[0:1], off
	s_add_i32 m0, s66, 0x1c000
	v_lshl_add_u64 v[0:1], s[38:39], 0, v[192:193]
	global_load_lds_dwordx4 v[0:1], off
	v_lshl_add_u64 v[0:1], s[38:39], 0, v[198:199]
	s_add_i32 m0, s66, 0x1e000
	s_cmpk_lt_u32 s4, 0x100
	global_load_lds_dwordx4 v[0:1], off
	v_and_b32_e32 v0, 48, v9
	v_lshlrev_b32_e32 v1, 6, v9
	v_and_or_b32 v0, v1, s44, v0
	v_lshlrev_b32_e32 v1, 2, v9
	v_and_b32_e32 v1, 32, v1
	v_bitop3_b32 v2, v0, s35, v1 bitop3:0xde
	v_bitop3_b32 v234, s5, v0, v1 bitop3:0xf6
	v_lshlrev_b32_e32 v0, 13, v13
	v_and_b32_e32 v0, 0xffffc000, v0
	v_lshl_add_u32 v0, v12, 10, v0
	v_and_b32_e32 v1, 1, v13
	v_lshl_or_b32 v0, v1, 6, v0
	s_cselect_b64 s[38:39], -1, 0
	s_cmpk_gt_u32 s40, 0xff
	v_lshl_add_u32 v204, v14, 1, v0
	v_lshlrev_b32_e32 v0, 13, v8
	s_cselect_b64 s[50:51], -1, 0
	s_lshl_b32 s4, s34, 11
	v_and_b32_e32 v0, 0xffffc000, v0
	s_waitcnt vmcnt(6)
	s_and_b32 s4, s4, 0x1800
	v_lshl_add_u32 v0, v10, 10, v0
	v_and_b32_e32 v1, 1, v8
	s_add_u32 s52, s26, s4
	v_lshl_or_b32 v0, v1, 6, v0
	s_addc_u32 s53, s27, 0
	v_mov_b32_e32 v205, v193
	v_lshl_add_u32 v206, v11, 1, v0
	v_mov_b32_e32 v207, v193
	s_mov_b32 s74, 0
	v_add_u32_e32 v235, 0, v2
	s_mov_b32 s75, s2
	s_mov_b32 s76, s12
	s_barrier
	s_mov_b32 s98, 0
	s_branch .LBB0_956
.Lfi_p4a_a:
	s_waitcnt vmcnt(40)
	s_branch .Lfi_p4a_aj

; #define PG8_STAGE(bufoff, gbase, voff) do { _Pragma("unroll") for (int _i = 0; _i < 2; ++_i) \
;         __builtin_amdgcn_global_load_lds((const unsigned*)((const char*)(gbase) + (voff)[_i]), (PG8_LAS unsigned*)(lds + (bufoff) + ldsw + _i * 8192), 16, 0, 0); } while (0)
; #define PG8_LDA(dst, b, h) do { _Pragma("unroll") for (int m = 0; m < 4; ++m) _Pragma("unroll") for (int k = 0; k < 2; ++k) dst[m][k] = *(const PG8_LAS bf16x8*)(lds + PG8_SA(b, h) + aoff + m * 2048 + k * 1024); } while (0)
; #define PG8_LDB(dst, b, h) do { _Pragma("unroll") for (int n = 0; n < 2; ++n) _Pragma("unroll") for (int k = 0; k < 2; ++k) dst[n][k] = *(const PG8_LAS bf16x8*)(lds + PG8_SB(b, h) + boff + n * 2048 + k * 1024); } while (0)
; #define PG8_MMA(ai, bj, At, Bt) do { __builtin_amdgcn_s_setprio(1); _Pragma("unroll") for (int m = 0; m < 4; ++m) _Pragma("unroll") for (int n = 0; n < 2; ++n) _Pragma("unroll") for (int k = 0; k < 2; ++k) \
;         acc[ai][bj][m][n] = __builtin_amdgcn_mfma_f32_16x16x32_bf16(Bt[n][k], At[m][k], acc[ai][bj][m][n], 0, 0, 0); __builtin_amdgcn_s_setprio(0); } while (0)
; #define PG8_WAIT_V(n) asm volatile("s_waitcnt vmcnt(" #n ")" ::: "memory")
; #define PG8_WAIT_L(n) asm volatile("s_waitcnt lgkmcnt(" #n ")" ::: "memory")
; #define PG8_BAR __builtin_amdgcn_s_barrier()
; #define PG8_SCHED __builtin_amdgcn_sched_barrier(0)
;     ...
;             const bool last = (t == nt - 2);
;             const char* a1 = cA + (size_t)(t + 1) * kstep;
;             const char* a2 = last ? nA : cA + (size_t)(t + 2) * kstep; const char* b2 = last ? nB : cB + (size_t)(t + 2) * kstep;
;             const char* a3 = a2 + kstep; const char* b3 = b2 + kstep;
;             if (last && has_next) S.a_ready(nxt);
;             if constexpr (SP2) {
;             PG8_LDB(B0, 0, 0); PG8_LDB(B1, 0, 1); PG8_SCHED; PG8_LDA(At, 0, 0); PG8_STAGE(PG8_SA(1, 1), a1 + hstepA, voffA);
;             PG8_WAIT_V(8); PG8_WAIT_L(0); PG8_BAR; PG8_MMA(0, 0, At, B0); PG8_MMA(0, 1, At, B1); PG8_BAR; PG8_SCHED;
;             PG8_LDA(At, 0, 1); PG8_STAGE(PG8_SB(0, 0), b2, voffB); PG8_STAGE(PG8_SB(0, 1), b2 + hstepB, voffB); PG8_STAGE(PG8_SA(0, 0), a2, voffA);
;             PG8_WAIT_V(8); PG8_WAIT_L(0); PG8_BAR; PG8_MMA(1, 0, At, B0); PG8_MMA(1, 1, At, B1); PG8_BAR; PG8_SCHED;
.LBB0_963:
	s_add_u32 s28, s6, 0xfffe0080
	s_addc_u32 s29, s7, -1
	s_add_i32 s48, 0, 0x10000
	s_cmp_eq_u32 s81, 4
	s_cselect_b32 s35, s57, s29
	s_cselect_b32 s34, s77, s28
	s_cselect_b32 s29, s55, s80
	s_cselect_b32 s28, s78, s79
	s_add_i32 s82, 0, 0x14000
	v_add_u32_e32 v92, s48, v234
	v_add_u32_e32 v132, s82, v234
	ds_read_b128 v[64:67], v92
	ds_read_b128 v[68:71], v92 offset:1024
	ds_read_b128 v[80:83], v92 offset:2048
	ds_read_b128 v[92:95], v92 offset:3072
	ds_read_b128 v[104:107], v132
	ds_read_b128 v[108:111], v132 offset:1024
	ds_read_b128 v[120:123], v132 offset:2048
	ds_read_b128 v[132:135], v132 offset:3072
	v_lshl_add_u64 v[208:209], s[6:7], 0, v[204:205]
	s_add_i32 m0, s66, 0xc000
	ds_read_b128 v[152:155], v235
	ds_read_b128 v[164:167], v235 offset:1024
	ds_read_b128 v[168:171], v235 offset:2048
	ds_read_b128 v[172:175], v235 offset:3072
	ds_read_b128 v[176:179], v235 offset:4096
	ds_read_b128 v[180:183], v235 offset:5120
	ds_read_b128 v[184:187], v235 offset:6144
	ds_read_b128 v[188:191], v235 offset:7168
	global_load_lds_dwordx4 v[208:209], off
	v_lshl_add_u64 v[208:209], s[6:7], 0, v[206:207]
	s_add_i32 m0, s66, 0xe000
	s_nop 0
	global_load_lds_dwordx4 v[208:209], off
	s_cmp_lg_u32 s98, 0
	s_cbranch_scc1 .Lfi_p4a_a
	s_waitcnt vmcnt(8)
.Lfi_p4a_aj:
	s_waitcnt lgkmcnt(0)
	s_barrier
	s_setprio 1
	s_waitcnt lgkmcnt(0)
	v_mfma_f32_16x16x32_bf16 v[160:163], v[64:67], v[152:155], v[160:163]
	v_mfma_f32_16x16x32_bf16 v[156:159], v[80:83], v[152:155], v[156:159]
	v_mfma_f32_16x16x32_bf16 v[140:143], v[64:67], v[168:171], v[140:143]
	v_mfma_f32_16x16x32_bf16 v[136:139], v[80:83], v[168:171], v[136:139]
	v_mfma_f32_16x16x32_bf16 v[116:119], v[64:67], v[176:179], v[116:119]
	v_mfma_f32_16x16x32_bf16 v[112:115], v[80:83], v[176:179], v[112:115]
	v_mfma_f32_16x16x32_bf16 v[88:91], v[64:67], v[184:187], v[88:91]
	v_mfma_f32_16x16x32_bf16 v[84:87], v[80:83], v[184:187], v[84:87]
	v_mfma_f32_16x16x32_bf16 v[160:163], v[68:71], v[164:167], v[160:163]
	v_mfma_f32_16x16x32_bf16 v[156:159], v[92:95], v[164:167], v[156:159]
	v_mfma_f32_16x16x32_bf16 v[140:143], v[68:71], v[172:175], v[140:143]
	v_mfma_f32_16x16x32_bf16 v[136:139], v[92:95], v[172:175], v[136:139]
	v_mfma_f32_16x16x32_bf16 v[116:119], v[68:71], v[180:183], v[116:119]
	v_mfma_f32_16x16x32_bf16 v[112:115], v[92:95], v[180:183], v[112:115]
	v_mfma_f32_16x16x32_bf16 v[88:91], v[68:71], v[188:191], v[88:91]
	v_mfma_f32_16x16x32_bf16 v[84:87], v[92:95], v[188:191], v[84:87]
	s_setprio 0
	s_setprio 1
	v_mfma_f32_16x16x32_bf16 v[148:151], v[104:107], v[152:155], v[148:151]
	v_mfma_f32_16x16x32_bf16 v[144:147], v[120:123], v[152:155], v[144:147]
	v_mfma_f32_16x16x32_bf16 v[128:131], v[104:107], v[168:171], v[128:131]
	v_mfma_f32_16x16x32_bf16 v[124:127], v[120:123], v[168:171], v[124:127]
	v_mfma_f32_16x16x32_bf16 v[100:103], v[104:107], v[176:179], v[100:103]
	v_mfma_f32_16x16x32_bf16 v[96:99], v[120:123], v[176:179], v[96:99]
	v_mfma_f32_16x16x32_bf16 v[76:79], v[104:107], v[184:187], v[76:79]
	v_mfma_f32_16x16x32_bf16 v[72:75], v[120:123], v[184:187], v[72:75]
	v_mfma_f32_16x16x32_bf16 v[148:151], v[108:111], v[164:167], v[148:151]
	v_mfma_f32_16x16x32_bf16 v[144:147], v[132:135], v[164:167], v[144:147]
	v_mfma_f32_16x16x32_bf16 v[128:131], v[108:111], v[172:175], v[128:131]
	v_mfma_f32_16x16x32_bf16 v[124:127], v[132:135], v[172:175], v[124:127]
	v_mfma_f32_16x16x32_bf16 v[100:103], v[108:111], v[180:183], v[100:103]
	v_mfma_f32_16x16x32_bf16 v[96:99], v[132:135], v[180:183], v[96:99]
	v_mfma_f32_16x16x32_bf16 v[76:79], v[108:111], v[188:191], v[76:79]
	v_mfma_f32_16x16x32_bf16 v[72:75], v[132:135], v[188:191], v[72:75]
	s_setprio 0
	s_barrier
	s_add_i32 s48, s48, s65
	v_lshl_add_u64 v[208:209], s[28:29], 0, v[192:193]
	s_mov_b32 m0, s48
	ds_read_b128 v[152:155], v235 offset:16384
	ds_read_b128 v[164:167], v235 offset:17408
	ds_read_b128 v[168:171], v235 offset:18432
	ds_read_b128 v[172:175], v235 offset:19456
	ds_read_b128 v[176:179], v235 offset:20480
	ds_read_b128 v[180:183], v235 offset:21504
	ds_read_b128 v[184:187], v235 offset:22528
	ds_read_b128 v[188:191], v235 offset:23552
	global_load_lds_dwordx4 v[208:209], off
	s_add_i32 m0, s48, 0x2000
	s_add_u32 s48, s28, 0x20000
	v_lshl_add_u64 v[210:211], s[28:29], 0, v[198:199]
	s_addc_u32 s49, s29, 0
	s_add_i32 s82, s82, s65
	global_load_lds_dwordx4 v[210:211], off
	v_lshl_add_u64 v[212:213], s[48:49], 0, v[192:193]
	s_mov_b32 m0, s82
	v_lshl_add_u64 v[214:215], s[34:35], 0, v[200:201]
	global_load_lds_dwordx4 v[212:213], off
	v_lshl_add_u64 v[212:213], s[48:49], 0, v[198:199]
	s_add_i32 m0, s82, 0x2000
	s_nop 0
	global_load_lds_dwordx4 v[212:213], off
	v_lshl_add_u64 v[212:213], s[34:35], 0, v[202:203]
	s_mov_b32 m0, s66
	s_nop 0
	global_load_lds_dwordx4 v[212:213], off
	s_mov_b32 m0, s67
	s_nop 0
	global_load_lds_dwordx4 v[214:215], off
	s_cmp_lg_u32 s98, 0
	s_cbranch_scc1 .Lfi_p4a_b
	s_waitcnt vmcnt(8)
; #define PG8_STAGE(bufoff, gbase, voff) do { _Pragma("unroll") for (int _i = 0; _i < 2; ++_i) \
;         __builtin_amdgcn_global_load_lds((const unsigned*)((const char*)(gbase) + (voff)[_i]), (PG8_LAS unsigned*)(lds + (bufoff) + ldsw + _i * 8192), 16, 0, 0); } while (0)
; #define PG8_LDA(dst, b, h) do { _Pragma("unroll") for (int m = 0; m < 4; ++m) _Pragma("unroll") for (int k = 0; k < 2; ++k) dst[m][k] = *(const PG8_LAS bf16x8*)(lds + PG8_SA(b, h) + aoff + m * 2048 + k * 1024); } while (0)
; #define PG8_LDB(dst, b, h) do { _Pragma("unroll") for (int n = 0; n < 2; ++n) _Pragma("unroll") for (int k = 0; k < 2; ++k) dst[n][k] = *(const PG8_LAS bf16x8*)(lds + PG8_SB(b, h) + boff + n * 2048 + k * 1024); } while (0)
; #define PG8_MMA(ai, bj, At, Bt) do { __builtin_amdgcn_s_setprio(1); _Pragma("unroll") for (int m = 0; m < 4; ++m) _Pragma("unroll") for (int n = 0; n < 2; ++n) _Pragma("unroll") for (int k = 0; k < 2; ++k) \
;         acc[ai][bj][m][n] = __builtin_amdgcn_mfma_f32_16x16x32_bf16(Bt[n][k], At[m][k], acc[ai][bj][m][n], 0, 0, 0); __builtin_amdgcn_s_setprio(0); } while (0)
; #define PG8_WAIT_V(n) asm volatile("s_waitcnt vmcnt(" #n ")" ::: "memory")
; #define PG8_WAIT_L(n) asm volatile("s_waitcnt lgkmcnt(" #n ")" ::: "memory")
; #define PG8_BAR __builtin_amdgcn_s_barrier()
; #define PG8_SCHED __builtin_amdgcn_sched_barrier(0)
;     ...
;             PG8_WAIT_V(8); PG8_WAIT_L(0); PG8_BAR; PG8_MMA(1, 0, At, B0); PG8_MMA(1, 1, At, B1); PG8_BAR; PG8_SCHED;
;             PG8_LDB(B0, 1, 0); PG8_LDB(B1, 1, 1); PG8_SCHED; PG8_LDA(At, 1, 0); PG8_STAGE(PG8_SA(0, 1), a2 + hstepA, voffA);
;             PG8_WAIT_V(8); PG8_WAIT_L(0); PG8_BAR; PG8_MMA(0, 0, At, B0); PG8_MMA(0, 1, At, B1); PG8_BAR; PG8_SCHED;
.Lfi_p4a_bj:
	s_mov_b32 s98, 0
	s_waitcnt lgkmcnt(0)
	s_barrier
	s_setprio 1
	s_waitcnt lgkmcnt(0)
	v_mfma_f32_16x16x32_bf16 v[60:63], v[64:67], v[152:155], v[60:63]
	v_mfma_f32_16x16x32_bf16 v[56:59], v[80:83], v[152:155], v[56:59]
	v_mfma_f32_16x16x32_bf16 v[44:47], v[64:67], v[168:171], v[44:47]
	v_mfma_f32_16x16x32_bf16 v[40:43], v[80:83], v[168:171], v[40:43]
	v_mfma_f32_16x16x32_bf16 v[28:31], v[64:67], v[176:179], v[28:31]
	v_mfma_f32_16x16x32_bf16 v[24:27], v[80:83], v[176:179], v[24:27]
	v_mfma_f32_16x16x32_bf16 v[12:15], v[64:67], v[184:187], v[12:15]
	v_mfma_f32_16x16x32_bf16 v[8:11], v[80:83], v[184:187], v[8:11]
	v_mfma_f32_16x16x32_bf16 v[60:63], v[68:71], v[164:167], v[60:63]
	v_mfma_f32_16x16x32_bf16 v[56:59], v[92:95], v[164:167], v[56:59]
	v_mfma_f32_16x16x32_bf16 v[44:47], v[68:71], v[172:175], v[44:47]
	v_mfma_f32_16x16x32_bf16 v[40:43], v[92:95], v[172:175], v[40:43]
	v_mfma_f32_16x16x32_bf16 v[28:31], v[68:71], v[180:183], v[28:31]
	v_mfma_f32_16x16x32_bf16 v[24:27], v[92:95], v[180:183], v[24:27]
	v_mfma_f32_16x16x32_bf16 v[12:15], v[68:71], v[188:191], v[12:15]
	v_mfma_f32_16x16x32_bf16 v[8:11], v[92:95], v[188:191], v[8:11]
	s_setprio 0
	s_setprio 1
	v_mfma_f32_16x16x32_bf16 v[52:55], v[104:107], v[152:155], v[52:55]
	v_mfma_f32_16x16x32_bf16 v[48:51], v[120:123], v[152:155], v[48:51]
	v_mfma_f32_16x16x32_bf16 v[36:39], v[104:107], v[168:171], v[36:39]
	v_mfma_f32_16x16x32_bf16 v[32:35], v[120:123], v[168:171], v[32:35]
	v_mfma_f32_16x16x32_bf16 v[20:23], v[104:107], v[176:179], v[20:23]
	v_mfma_f32_16x16x32_bf16 v[16:19], v[120:123], v[176:179], v[16:19]
	v_mfma_f32_16x16x32_bf16 v[4:7], v[104:107], v[184:187], v[4:7]
	v_mfma_f32_16x16x32_bf16 v[0:3], v[120:123], v[184:187], v[0:3]
	v_mfma_f32_16x16x32_bf16 v[52:55], v[108:111], v[164:167], v[52:55]
	v_mfma_f32_16x16x32_bf16 v[48:51], v[132:135], v[164:167], v[48:51]
	v_mfma_f32_16x16x32_bf16 v[36:39], v[108:111], v[172:175], v[36:39]
	v_mfma_f32_16x16x32_bf16 v[32:35], v[132:135], v[172:175], v[32:35]
	v_mfma_f32_16x16x32_bf16 v[20:23], v[108:111], v[180:183], v[20:23]
	v_mfma_f32_16x16x32_bf16 v[16:19], v[132:135], v[180:183], v[16:19]
	v_mfma_f32_16x16x32_bf16 v[4:7], v[108:111], v[188:191], v[4:7]
	v_mfma_f32_16x16x32_bf16 v[0:3], v[132:135], v[188:191], v[0:3]
	s_setprio 0
	s_barrier
	s_add_i32 s48, 0, 0x18000
	s_add_i32 s49, 0, 0x1c000
	v_add_u32_e32 v92, s48, v234
	v_add_u32_e32 v132, s49, v234
	ds_read_b128 v[64:67], v92
	ds_read_b128 v[68:71], v92 offset:1024
	ds_read_b128 v[80:83], v92 offset:2048
	ds_read_b128 v[92:95], v92 offset:3072
	ds_read_b128 v[104:107], v132
	ds_read_b128 v[108:111], v132 offset:1024
	ds_read_b128 v[120:123], v132 offset:2048
	ds_read_b128 v[132:135], v132 offset:3072
	s_add_u32 s34, s34, 0x20000
	s_addc_u32 s35, s35, 0
	s_mov_b32 m0, s68
	v_lshl_add_u64 v[216:217], s[34:35], 0, v[202:203]
	ds_read_b128 v[152:155], v235 offset:32768
	ds_read_b128 v[164:167], v235 offset:33792
	ds_read_b128 v[168:171], v235 offset:34816
	ds_read_b128 v[172:175], v235 offset:35840
	ds_read_b128 v[176:179], v235 offset:36864
	ds_read_b128 v[180:183], v235 offset:37888
	ds_read_b128 v[184:187], v235 offset:38912
	ds_read_b128 v[188:191], v235 offset:39936
	global_load_lds_dwordx4 v[216:217], off
	v_lshl_add_u64 v[216:217], s[34:35], 0, v[200:201]
	s_mov_b32 m0, s69
	s_nop 0
	global_load_lds_dwordx4 v[216:217], off
	s_waitcnt vmcnt(8)
	s_waitcnt lgkmcnt(0)
	s_barrier
	s_setprio 1
	s_waitcnt lgkmcnt(0)
	v_mfma_f32_16x16x32_bf16 v[160:163], v[64:67], v[152:155], v[160:163]
	v_mfma_f32_16x16x32_bf16 v[156:159], v[80:83], v[152:155], v[156:159]
	v_mfma_f32_16x16x32_bf16 v[140:143], v[64:67], v[168:171], v[140:143]
	v_mfma_f32_16x16x32_bf16 v[136:139], v[80:83], v[168:171], v[136:139]
	v_mfma_f32_16x16x32_bf16 v[116:119], v[64:67], v[176:179], v[116:119]
	v_mfma_f32_16x16x32_bf16 v[112:115], v[80:83], v[176:179], v[112:115]
	v_mfma_f32_16x16x32_bf16 v[88:91], v[64:67], v[184:187], v[88:91]
	v_mfma_f32_16x16x32_bf16 v[84:87], v[80:83], v[184:187], v[84:87]
	v_mfma_f32_16x16x32_bf16 v[160:163], v[68:71], v[164:167], v[160:163]
	v_mfma_f32_16x16x32_bf16 v[156:159], v[92:95], v[164:167], v[156:159]
	v_mfma_f32_16x16x32_bf16 v[140:143], v[68:71], v[172:175], v[140:143]
	v_mfma_f32_16x16x32_bf16 v[136:139], v[92:95], v[172:175], v[136:139]
	v_mfma_f32_16x16x32_bf16 v[116:119], v[68:71], v[180:183], v[116:119]
	v_mfma_f32_16x16x32_bf16 v[112:115], v[92:95], v[180:183], v[112:115]
	v_mfma_f32_16x16x32_bf16 v[88:91], v[68:71], v[188:191], v[88:91]
	v_mfma_f32_16x16x32_bf16 v[84:87], v[92:95], v[188:191], v[84:87]
	s_setprio 0
	s_setprio 1
	v_mfma_f32_16x16x32_bf16 v[148:151], v[104:107], v[152:155], v[148:151]
	v_mfma_f32_16x16x32_bf16 v[144:147], v[120:123], v[152:155], v[144:147]
	v_mfma_f32_16x16x32_bf16 v[128:131], v[104:107], v[168:171], v[128:131]
	v_mfma_f32_16x16x32_bf16 v[124:127], v[120:123], v[168:171], v[124:127]
	v_mfma_f32_16x16x32_bf16 v[100:103], v[104:107], v[176:179], v[100:103]
	v_mfma_f32_16x16x32_bf16 v[96:99], v[120:123], v[176:179], v[96:99]
	v_mfma_f32_16x16x32_bf16 v[76:79], v[104:107], v[184:187], v[76:79]
	v_mfma_f32_16x16x32_bf16 v[72:75], v[120:123], v[184:187], v[72:75]
	v_mfma_f32_16x16x32_bf16 v[148:151], v[108:111], v[164:167], v[148:151]
	v_mfma_f32_16x16x32_bf16 v[144:147], v[132:135], v[164:167], v[144:147]
	v_mfma_f32_16x16x32_bf16 v[128:131], v[108:111], v[172:175], v[128:131]
	v_mfma_f32_16x16x32_bf16 v[124:127], v[132:135], v[172:175], v[124:127]
	v_mfma_f32_16x16x32_bf16 v[100:103], v[108:111], v[180:183], v[100:103]
	v_mfma_f32_16x16x32_bf16 v[96:99], v[132:135], v[180:183], v[96:99]
	v_mfma_f32_16x16x32_bf16 v[76:79], v[108:111], v[188:191], v[76:79]
	v_mfma_f32_16x16x32_bf16 v[72:75], v[132:135], v[188:191], v[72:75]
	s_setprio 0
	s_barrier
; #define PG8_STAGE(bufoff, gbase, voff) do { _Pragma("unroll") for (int _i = 0; _i < 2; ++_i) \
;         __builtin_amdgcn_global_load_lds((const unsigned*)((const char*)(gbase) + (voff)[_i]), (PG8_LAS unsigned*)(lds + (bufoff) + ldsw + _i * 8192), 16, 0, 0); } while (0)
; #define PG8_LDA(dst, b, h) do { _Pragma("unroll") for (int m = 0; m < 4; ++m) _Pragma("unroll") for (int k = 0; k < 2; ++k) dst[m][k] = *(const PG8_LAS bf16x8*)(lds + PG8_SA(b, h) + aoff + m * 2048 + k * 1024); } while (0)
; #define PG8_MMA(ai, bj, At, Bt) do { __builtin_amdgcn_s_setprio(1); _Pragma("unroll") for (int m = 0; m < 4; ++m) _Pragma("unroll") for (int n = 0; n < 2; ++n) _Pragma("unroll") for (int k = 0; k < 2; ++k) \
;         acc[ai][bj][m][n] = __builtin_amdgcn_mfma_f32_16x16x32_bf16(Bt[n][k], At[m][k], acc[ai][bj][m][n], 0, 0, 0); __builtin_amdgcn_s_setprio(0); } while (0)
; #define PG8_WAIT_V(n) asm volatile("s_waitcnt vmcnt(" #n ")" ::: "memory")
; #define PG8_WAIT_L(n) asm volatile("s_waitcnt lgkmcnt(" #n ")" ::: "memory")
; #define PG8_BAR __builtin_amdgcn_s_barrier()
; #define PG8_SCHED __builtin_amdgcn_sched_barrier(0)
;     ...
;         for (int t = 0; t < nt; t += 2) {
;     ...
;             PG8_LDA(At, 1, 1); PG8_STAGE(PG8_SB(1, 0), b3, voffB); PG8_STAGE(PG8_SB(1, 1), b3 + hstepB, voffB); PG8_STAGE(PG8_SA(1, 0), a3, voffA);
;             PG8_WAIT_V(8); PG8_WAIT_L(0); PG8_BAR; PG8_MMA(1, 0, At, B0); PG8_MMA(1, 1, At, B1); PG8_BAR; PG8_SCHED;
	s_add_i32 s34, s48, s65
	v_lshl_add_u64 v[208:209], v[208:209], 0, s[22:23]
	s_mov_b32 m0, s34
	ds_read_b128 v[152:155], v235 offset:49152
	ds_read_b128 v[164:167], v235 offset:50176
	ds_read_b128 v[168:171], v235 offset:51200
	ds_read_b128 v[172:175], v235 offset:52224
	ds_read_b128 v[176:179], v235 offset:53248
	ds_read_b128 v[180:183], v235 offset:54272
	ds_read_b128 v[184:187], v235 offset:55296
	ds_read_b128 v[188:191], v235 offset:56320
	global_load_lds_dwordx4 v[208:209], off
	s_add_i32 m0, s34, 0x2000
	s_add_u32 s28, s28, 0x20080
	v_lshl_add_u64 v[208:209], v[210:211], 0, s[22:23]
	s_addc_u32 s29, s29, 0
	s_add_i32 s34, s49, s65
	global_load_lds_dwordx4 v[208:209], off
	v_lshl_add_u64 v[208:209], s[28:29], 0, v[192:193]
	s_mov_b32 m0, s34
	s_nop 0
	global_load_lds_dwordx4 v[208:209], off
	v_lshl_add_u64 v[208:209], s[28:29], 0, v[198:199]
	s_add_i32 m0, s34, 0x2000
	s_nop 0
	global_load_lds_dwordx4 v[208:209], off
	v_lshl_add_u64 v[208:209], v[212:213], 0, s[22:23]
	s_mov_b32 m0, s72
	s_nop 0
	global_load_lds_dwordx4 v[208:209], off
	v_lshl_add_u64 v[208:209], v[214:215], 0, s[22:23]
	s_mov_b32 m0, s73
	s_nop 0
	global_load_lds_dwordx4 v[208:209], off
	s_waitcnt vmcnt(8)
	s_waitcnt lgkmcnt(0)
	s_barrier
	s_setprio 1
	s_waitcnt lgkmcnt(0)
	v_mfma_f32_16x16x32_bf16 v[60:63], v[64:67], v[152:155], v[60:63]
	v_mfma_f32_16x16x32_bf16 v[56:59], v[80:83], v[152:155], v[56:59]
	v_mfma_f32_16x16x32_bf16 v[44:47], v[64:67], v[168:171], v[44:47]
	v_mfma_f32_16x16x32_bf16 v[40:43], v[80:83], v[168:171], v[40:43]
	v_mfma_f32_16x16x32_bf16 v[28:31], v[64:67], v[176:179], v[28:31]
	v_mfma_f32_16x16x32_bf16 v[24:27], v[80:83], v[176:179], v[24:27]
	v_mfma_f32_16x16x32_bf16 v[12:15], v[64:67], v[184:187], v[12:15]
	v_mfma_f32_16x16x32_bf16 v[8:11], v[80:83], v[184:187], v[8:11]
	v_mfma_f32_16x16x32_bf16 v[60:63], v[68:71], v[164:167], v[60:63]
	v_mfma_f32_16x16x32_bf16 v[56:59], v[92:95], v[164:167], v[56:59]
	v_mfma_f32_16x16x32_bf16 v[44:47], v[68:71], v[172:175], v[44:47]
	v_mfma_f32_16x16x32_bf16 v[40:43], v[92:95], v[172:175], v[40:43]
	v_mfma_f32_16x16x32_bf16 v[28:31], v[68:71], v[180:183], v[28:31]
	v_mfma_f32_16x16x32_bf16 v[24:27], v[92:95], v[180:183], v[24:27]
	v_mfma_f32_16x16x32_bf16 v[12:15], v[68:71], v[188:191], v[12:15]
	v_mfma_f32_16x16x32_bf16 v[8:11], v[92:95], v[188:191], v[8:11]
	s_setprio 0
	s_setprio 1
	v_mfma_f32_16x16x32_bf16 v[52:55], v[104:107], v[152:155], v[52:55]
	v_mfma_f32_16x16x32_bf16 v[48:51], v[120:123], v[152:155], v[48:51]
	v_mfma_f32_16x16x32_bf16 v[36:39], v[104:107], v[168:171], v[36:39]
	v_mfma_f32_16x16x32_bf16 v[32:35], v[120:123], v[168:171], v[32:35]
	v_mfma_f32_16x16x32_bf16 v[20:23], v[104:107], v[176:179], v[20:23]
	v_mfma_f32_16x16x32_bf16 v[16:19], v[120:123], v[176:179], v[16:19]
	v_mfma_f32_16x16x32_bf16 v[4:7], v[104:107], v[184:187], v[4:7]
	v_mfma_f32_16x16x32_bf16 v[0:3], v[120:123], v[184:187], v[0:3]
	v_mfma_f32_16x16x32_bf16 v[52:55], v[108:111], v[164:167], v[52:55]
	v_mfma_f32_16x16x32_bf16 v[48:51], v[132:135], v[164:167], v[48:51]
	v_mfma_f32_16x16x32_bf16 v[36:39], v[108:111], v[172:175], v[36:39]
	v_mfma_f32_16x16x32_bf16 v[32:35], v[132:135], v[172:175], v[32:35]
	v_mfma_f32_16x16x32_bf16 v[20:23], v[108:111], v[180:183], v[20:23]
	v_mfma_f32_16x16x32_bf16 v[16:19], v[132:135], v[180:183], v[16:19]
	v_mfma_f32_16x16x32_bf16 v[4:7], v[108:111], v[188:191], v[4:7]
	v_mfma_f32_16x16x32_bf16 v[0:3], v[132:135], v[188:191], v[0:3]
	s_setprio 0
	s_barrier
	s_add_i32 s81, s81, 2
	s_add_u32 s6, s6, 0x100
	s_addc_u32 s7, s7, 0
	s_add_u32 s79, s79, 0x100
	s_addc_u32 s80, s80, 0
	s_cmp_gt_u32 s81, 5
	s_cbranch_scc0 .LBB0_963
	s_mov_b32 s98, 1
	s_and_b64 vcc, exec, s[38:39]
	s_cbranch_vccz .LBB0_966
	s_barrier

; #define PG8_STAGE(bufoff, gbase, voff) do { _Pragma("unroll") for (int _i = 0; _i < 2; ++_i) \
;         __builtin_amdgcn_global_load_lds((const unsigned*)((const char*)(gbase) + (voff)[_i]), (PG8_LAS unsigned*)(lds + (bufoff) + ldsw + _i * 8192), 16, 0, 0); } while (0)
; #define PG8_WAIT_V(n) asm volatile("s_waitcnt vmcnt(" #n ")" ::: "memory")
; #define PG8_BAR __builtin_amdgcn_s_barrier()
;     ...
;     for (int i = 0; i < 2; ++i) { int R, C; stage_rc(tid * 16 + i * 8192, R, C); const int Rb = Epi::PERM ? ((R & ~31) + perm32(R & 31)) : R;
;         voffA[i] = (unsigned)(R * lda_ + C) * 2u; voffB[i] = (unsigned)(Rb * K + C) * 2u; }
;     const size_t kstep = (size_t)(BK * 2);
;     const size_t hstepA = (size_t)HALF * lda_ * 2, hstepB = (size_t)HALF * K * 2;
;     const size_t tstepA = 2 * hstepA, tstepB = 2 * hstepB;
;     const unsigned ldsw = (unsigned)wid * 1024u;
;     const int aoff = lds_byte(wr * 64 + fr, fq * 8), boff = lds_byte(wc * 32 + fr, fq * 8);
;     ...
;         PG8_STAGE(PG8_SB(1, 0), cB + kstep, voffB); PG8_STAGE(PG8_SA(1, 0), cA + kstep, voffA); PG8_STAGE(PG8_SB(1, 1), cB + hstepB + kstep, voffB);
;         PG8_WAIT_V(6); PG8_BAR;
.LBB0_1071:
	s_lshl_b32 s5, s5, 5
	s_and_b32 s66, s5, 0x60
	s_add_i32 m0, s61, 0x18000
	v_lshl_add_u64 v[6:7], v[6:7], 0, s[22:23]
	s_lshl_b32 s65, s6, 6
	s_lshl_b32 s36, s6, 13
	s_lshl_b32 s5, s66, 7
	s_waitcnt vmcnt(2)
	s_barrier
	global_load_lds_dwordx4 v[6:7], off
	v_lshl_add_u64 v[4:5], v[4:5], 0, s[22:23]
	s_add_i32 m0, s61, 0x1a000
	s_add_i32 s67, s61, 0x8000
	s_add_i32 s68, s61, 0xa000
	global_load_lds_dwordx4 v[4:5], off
	v_lshl_add_u64 v[0:1], v[0:1], 0, s[22:23]
	s_mov_b32 m0, s67
	s_add_u32 s6, s34, 0x40080
	global_load_lds_dwordx4 v[0:1], off
	v_lshl_add_u64 v[0:1], v[2:3], 0, s[22:23]
	s_mov_b32 m0, s68
	s_addc_u32 s7, s35, 0
	global_load_lds_dwordx4 v[0:1], off
	s_add_i32 m0, s61, 0x1c000
	v_lshl_add_u64 v[0:1], s[6:7], 0, v[192:193]
	global_load_lds_dwordx4 v[0:1], off
	v_lshl_add_u64 v[0:1], s[6:7], 0, v[198:199]
	s_add_i32 m0, s61, 0x1e000
	s_cmpk_lt_u32 s4, 0x100
	global_load_lds_dwordx4 v[0:1], off
	v_and_b32_e32 v0, 48, v9
	v_lshlrev_b32_e32 v1, 6, v9
	v_and_or_b32 v0, v1, s44, v0
	v_lshlrev_b32_e32 v1, 2, v9
	v_and_b32_e32 v1, 32, v1
	v_bitop3_b32 v2, v0, s36, v1 bitop3:0xde
	v_bitop3_b32 v234, s5, v0, v1 bitop3:0xf6
	v_lshrrev_b32_e32 v1, 1, v14
	v_mul_lo_u32 v0, v13, s47
	v_mad_u64_u32 v[0:1], s[4:5], v1, s43, v[0:1]
	v_or_b32_e32 v0, v0, v15
	v_add_lshl_u32 v0, v0, v16, 1
	v_mov_b32_e32 v1, v193
	v_lshl_add_u64 v[204:205], v[0:1], 0, s[24:25]
	v_lshrrev_b32_e32 v1, 1, v8
	v_mul_lo_u32 v0, v10, s47
	v_mad_u64_u32 v[0:1], s[4:5], v1, s43, v[0:1]
	s_waitcnt vmcnt(6)
	v_or_b32_e32 v0, v0, v11
	s_cselect_b64 s[36:37], -1, 0
	s_cmpk_gt_u32 s40, 0xff
	v_add_lshl_u32 v0, v0, v12, 1
	v_mov_b32_e32 v1, v193
	s_cselect_b64 s[38:39], -1, 0
	v_lshl_add_u64 v[206:207], v[0:1], 0, s[24:25]
	s_mov_b32 s69, 0
	v_add_u32_e32 v235, 0, v2
	s_mov_b32 s71, s2
	s_mov_b32 s72, s12
	s_barrier
	s_mov_b32 s98, 0
	s_branch .LBB0_1074

; #define PG8_STAGE(bufoff, gbase, voff) do { _Pragma("unroll") for (int _i = 0; _i < 2; ++_i) \
;         __builtin_amdgcn_global_load_lds((const unsigned*)((const char*)(gbase) + (voff)[_i]), (PG8_LAS unsigned*)(lds + (bufoff) + ldsw + _i * 8192), 16, 0, 0); } while (0)
; #define PG8_LDA(dst, b, h) do { _Pragma("unroll") for (int m = 0; m < 4; ++m) _Pragma("unroll") for (int k = 0; k < 2; ++k) dst[m][k] = *(const PG8_LAS bf16x8*)(lds + PG8_SA(b, h) + aoff + m * 2048 + k * 1024); } while (0)
; #define PG8_LDB(dst, b, h) do { _Pragma("unroll") for (int n = 0; n < 2; ++n) _Pragma("unroll") for (int k = 0; k < 2; ++k) dst[n][k] = *(const PG8_LAS bf16x8*)(lds + PG8_SB(b, h) + boff + n * 2048 + k * 1024); } while (0)
; #define PG8_MMA(ai, bj, At, Bt) do { __builtin_amdgcn_s_setprio(1); _Pragma("unroll") for (int m = 0; m < 4; ++m) _Pragma("unroll") for (int n = 0; n < 2; ++n) _Pragma("unroll") for (int k = 0; k < 2; ++k) \
;         acc[ai][bj][m][n] = __builtin_amdgcn_mfma_f32_16x16x32_bf16(Bt[n][k], At[m][k], acc[ai][bj][m][n], 0, 0, 0); __builtin_amdgcn_s_setprio(0); } while (0)
; #define PG8_WAIT_V(n) asm volatile("s_waitcnt vmcnt(" #n ")" ::: "memory")
; #define PG8_WAIT_L(n) asm volatile("s_waitcnt lgkmcnt(" #n ")" ::: "memory")
; #define PG8_BAR __builtin_amdgcn_s_barrier()
; #define PG8_SCHED __builtin_amdgcn_sched_barrier(0)
;     ...
;             const char* a2 = last ? nA : cA + (size_t)(t + 2) * kstep; const char* b2 = last ? nB : cB + (size_t)(t + 2) * kstep;
;             const char* a3 = a2 + kstep; const char* b3 = b2 + kstep;
;             if (last && has_next) S.a_ready(nxt);
;             if constexpr (SP2) {
;             PG8_LDB(B0, 0, 0); PG8_LDB(B1, 0, 1); PG8_SCHED; PG8_LDA(At, 0, 0); PG8_STAGE(PG8_SA(1, 1), a1 + hstepA, voffA);
;             PG8_WAIT_V(8); PG8_WAIT_L(0); PG8_BAR; PG8_MMA(0, 0, At, B0); PG8_MMA(0, 1, At, B1); PG8_BAR; PG8_SCHED;
;             PG8_LDA(At, 0, 1); PG8_STAGE(PG8_SB(0, 0), b2, voffB); PG8_STAGE(PG8_SB(0, 1), b2 + hstepB, voffB); PG8_STAGE(PG8_SA(0, 0), a2, voffA);
.LBB0_1083:
	s_add_u32 s6, s28, 0x100
	s_addc_u32 s7, s29, 0
	s_add_i32 s48, 0, 0x10000
	s_cmp_eq_u32 s76, 12
	s_cselect_b32 s41, s53, s7
	s_cselect_b32 s40, s52, s6
	s_cselect_b32 s35, s51, s75
	s_cselect_b32 s34, s73, s74
	s_add_i32 s49, 0, 0x14000
	v_add_u32_e32 v92, s48, v234
	v_add_u32_e32 v132, s49, v234
	ds_read_b128 v[64:67], v92
	ds_read_b128 v[68:71], v92 offset:1024
	ds_read_b128 v[80:83], v92 offset:2048
	ds_read_b128 v[92:95], v92 offset:3072
	ds_read_b128 v[104:107], v132
	ds_read_b128 v[108:111], v132 offset:1024
	ds_read_b128 v[120:123], v132 offset:2048
	ds_read_b128 v[132:135], v132 offset:3072
	v_lshl_add_u64 v[208:209], s[28:29], 0, v[204:205]
	s_add_i32 m0, s61, 0xc000
	ds_read_b128 v[152:155], v235
	ds_read_b128 v[164:167], v235 offset:1024
	ds_read_b128 v[168:171], v235 offset:2048
	ds_read_b128 v[172:175], v235 offset:3072
	ds_read_b128 v[176:179], v235 offset:4096
	ds_read_b128 v[180:183], v235 offset:5120
	ds_read_b128 v[184:187], v235 offset:6144
	ds_read_b128 v[188:191], v235 offset:7168
	global_load_lds_dwordx4 v[208:209], off
	v_lshl_add_u64 v[208:209], s[28:29], 0, v[206:207]
	s_add_i32 m0, s61, 0xe000
	s_nop 0
	global_load_lds_dwordx4 v[208:209], off
	s_cmp_lg_u32 s98, 0
	s_cbranch_scc1 .Lfi_p4b_a
	s_waitcnt vmcnt(8)
.Lfi_p4b_aj:
	s_waitcnt lgkmcnt(0)
	s_barrier
	s_setprio 1
	s_waitcnt lgkmcnt(0)
	v_mfma_f32_16x16x32_bf16 v[160:163], v[64:67], v[152:155], v[160:163]
	v_mfma_f32_16x16x32_bf16 v[156:159], v[80:83], v[152:155], v[156:159]
	v_mfma_f32_16x16x32_bf16 v[140:143], v[64:67], v[168:171], v[140:143]
	v_mfma_f32_16x16x32_bf16 v[136:139], v[80:83], v[168:171], v[136:139]
	v_mfma_f32_16x16x32_bf16 v[116:119], v[64:67], v[176:179], v[116:119]
	v_mfma_f32_16x16x32_bf16 v[112:115], v[80:83], v[176:179], v[112:115]
	v_mfma_f32_16x16x32_bf16 v[88:91], v[64:67], v[184:187], v[88:91]
	v_mfma_f32_16x16x32_bf16 v[84:87], v[80:83], v[184:187], v[84:87]
	v_mfma_f32_16x16x32_bf16 v[160:163], v[68:71], v[164:167], v[160:163]
	v_mfma_f32_16x16x32_bf16 v[156:159], v[92:95], v[164:167], v[156:159]
	v_mfma_f32_16x16x32_bf16 v[140:143], v[68:71], v[172:175], v[140:143]
	v_mfma_f32_16x16x32_bf16 v[136:139], v[92:95], v[172:175], v[136:139]
	v_mfma_f32_16x16x32_bf16 v[116:119], v[68:71], v[180:183], v[116:119]
	v_mfma_f32_16x16x32_bf16 v[112:115], v[92:95], v[180:183], v[112:115]
	v_mfma_f32_16x16x32_bf16 v[88:91], v[68:71], v[188:191], v[88:91]
	v_mfma_f32_16x16x32_bf16 v[84:87], v[92:95], v[188:191], v[84:87]
	s_setprio 0
	s_setprio 1
	v_mfma_f32_16x16x32_bf16 v[148:151], v[104:107], v[152:155], v[148:151]
	v_mfma_f32_16x16x32_bf16 v[144:147], v[120:123], v[152:155], v[144:147]
	v_mfma_f32_16x16x32_bf16 v[128:131], v[104:107], v[168:171], v[128:131]
	v_mfma_f32_16x16x32_bf16 v[124:127], v[120:123], v[168:171], v[124:127]
	v_mfma_f32_16x16x32_bf16 v[100:103], v[104:107], v[176:179], v[100:103]
	v_mfma_f32_16x16x32_bf16 v[96:99], v[120:123], v[176:179], v[96:99]
	v_mfma_f32_16x16x32_bf16 v[76:79], v[104:107], v[184:187], v[76:79]
	v_mfma_f32_16x16x32_bf16 v[72:75], v[120:123], v[184:187], v[72:75]
	v_mfma_f32_16x16x32_bf16 v[148:151], v[108:111], v[164:167], v[148:151]
	v_mfma_f32_16x16x32_bf16 v[144:147], v[132:135], v[164:167], v[144:147]
	v_mfma_f32_16x16x32_bf16 v[128:131], v[108:111], v[172:175], v[128:131]
	v_mfma_f32_16x16x32_bf16 v[124:127], v[132:135], v[172:175], v[124:127]
	v_mfma_f32_16x16x32_bf16 v[100:103], v[108:111], v[180:183], v[100:103]
	v_mfma_f32_16x16x32_bf16 v[96:99], v[132:135], v[180:183], v[96:99]
	v_mfma_f32_16x16x32_bf16 v[76:79], v[108:111], v[188:191], v[76:79]
	v_mfma_f32_16x16x32_bf16 v[72:75], v[132:135], v[188:191], v[72:75]
	s_setprio 0
	s_barrier
	s_add_i32 s28, s48, s58
	v_lshl_add_u64 v[208:209], s[34:35], 0, v[192:193]
	s_mov_b32 m0, s28
	ds_read_b128 v[152:155], v235 offset:16384
	ds_read_b128 v[164:167], v235 offset:17408
	ds_read_b128 v[168:171], v235 offset:18432
	ds_read_b128 v[172:175], v235 offset:19456
	ds_read_b128 v[176:179], v235 offset:20480
	ds_read_b128 v[180:183], v235 offset:21504
	ds_read_b128 v[184:187], v235 offset:22528
	ds_read_b128 v[188:191], v235 offset:23552
	global_load_lds_dwordx4 v[208:209], off
	s_add_i32 m0, s28, 0x2000
	s_add_u32 s28, s34, 0x40000
	v_lshl_add_u64 v[210:211], s[34:35], 0, v[198:199]
	s_addc_u32 s29, s35, 0
	s_add_i32 s48, s49, s58
	global_load_lds_dwordx4 v[210:211], off
	v_lshl_add_u64 v[212:213], s[28:29], 0, v[192:193]
	s_mov_b32 m0, s48
	v_lshl_add_u64 v[214:215], s[40:41], 0, v[200:201]
	global_load_lds_dwordx4 v[212:213], off
	v_lshl_add_u64 v[212:213], s[28:29], 0, v[198:199]
	s_add_i32 m0, s48, 0x2000
	s_nop 0
	global_load_lds_dwordx4 v[212:213], off
	v_lshl_add_u64 v[212:213], s[40:41], 0, v[202:203]
	s_mov_b32 m0, s61
	s_nop 0
	global_load_lds_dwordx4 v[212:213], off
	s_mov_b32 m0, s62
	s_nop 0
	global_load_lds_dwordx4 v[214:215], off
	s_cmp_lg_u32 s98, 0
	s_cbranch_scc1 .Lfi_p4b_b
	s_waitcnt vmcnt(8)
; #define PG8_STAGE(bufoff, gbase, voff) do { _Pragma("unroll") for (int _i = 0; _i < 2; ++_i) \
;         __builtin_amdgcn_global_load_lds((const unsigned*)((const char*)(gbase) + (voff)[_i]), (PG8_LAS unsigned*)(lds + (bufoff) + ldsw + _i * 8192), 16, 0, 0); } while (0)
; #define PG8_LDA(dst, b, h) do { _Pragma("unroll") for (int m = 0; m < 4; ++m) _Pragma("unroll") for (int k = 0; k < 2; ++k) dst[m][k] = *(const PG8_LAS bf16x8*)(lds + PG8_SA(b, h) + aoff + m * 2048 + k * 1024); } while (0)
; #define PG8_LDB(dst, b, h) do { _Pragma("unroll") for (int n = 0; n < 2; ++n) _Pragma("unroll") for (int k = 0; k < 2; ++k) dst[n][k] = *(const PG8_LAS bf16x8*)(lds + PG8_SB(b, h) + boff + n * 2048 + k * 1024); } while (0)
; #define PG8_MMA(ai, bj, At, Bt) do { __builtin_amdgcn_s_setprio(1); _Pragma("unroll") for (int m = 0; m < 4; ++m) _Pragma("unroll") for (int n = 0; n < 2; ++n) _Pragma("unroll") for (int k = 0; k < 2; ++k) \
;         acc[ai][bj][m][n] = __builtin_amdgcn_mfma_f32_16x16x32_bf16(Bt[n][k], At[m][k], acc[ai][bj][m][n], 0, 0, 0); __builtin_amdgcn_s_setprio(0); } while (0)
; #define PG8_WAIT_V(n) asm volatile("s_waitcnt vmcnt(" #n ")" ::: "memory")
; #define PG8_WAIT_L(n) asm volatile("s_waitcnt lgkmcnt(" #n ")" ::: "memory")
; #define PG8_BAR __builtin_amdgcn_s_barrier()
; #define PG8_SCHED __builtin_amdgcn_sched_barrier(0)
;     ...
;             PG8_WAIT_V(8); PG8_WAIT_L(0); PG8_BAR; PG8_MMA(1, 0, At, B0); PG8_MMA(1, 1, At, B1); PG8_BAR; PG8_SCHED;
;             PG8_LDB(B0, 1, 0); PG8_LDB(B1, 1, 1); PG8_SCHED; PG8_LDA(At, 1, 0); PG8_STAGE(PG8_SA(0, 1), a2 + hstepA, voffA);
;             PG8_WAIT_V(8); PG8_WAIT_L(0); PG8_BAR; PG8_MMA(0, 0, At, B0); PG8_MMA(0, 1, At, B1); PG8_BAR; PG8_SCHED;
.Lfi_p4b_bj:
	s_mov_b32 s98, 0
	s_waitcnt lgkmcnt(0)
	s_barrier
	s_setprio 1
	s_waitcnt lgkmcnt(0)
	v_mfma_f32_16x16x32_bf16 v[60:63], v[64:67], v[152:155], v[60:63]
	v_mfma_f32_16x16x32_bf16 v[56:59], v[80:83], v[152:155], v[56:59]
	v_mfma_f32_16x16x32_bf16 v[44:47], v[64:67], v[168:171], v[44:47]
	v_mfma_f32_16x16x32_bf16 v[40:43], v[80:83], v[168:171], v[40:43]
	v_mfma_f32_16x16x32_bf16 v[28:31], v[64:67], v[176:179], v[28:31]
	v_mfma_f32_16x16x32_bf16 v[24:27], v[80:83], v[176:179], v[24:27]
	v_mfma_f32_16x16x32_bf16 v[12:15], v[64:67], v[184:187], v[12:15]
	v_mfma_f32_16x16x32_bf16 v[8:11], v[80:83], v[184:187], v[8:11]
	v_mfma_f32_16x16x32_bf16 v[60:63], v[68:71], v[164:167], v[60:63]
	v_mfma_f32_16x16x32_bf16 v[56:59], v[92:95], v[164:167], v[56:59]
	v_mfma_f32_16x16x32_bf16 v[44:47], v[68:71], v[172:175], v[44:47]
	v_mfma_f32_16x16x32_bf16 v[40:43], v[92:95], v[172:175], v[40:43]
	v_mfma_f32_16x16x32_bf16 v[28:31], v[68:71], v[180:183], v[28:31]
	v_mfma_f32_16x16x32_bf16 v[24:27], v[92:95], v[180:183], v[24:27]
	v_mfma_f32_16x16x32_bf16 v[12:15], v[68:71], v[188:191], v[12:15]
	v_mfma_f32_16x16x32_bf16 v[8:11], v[92:95], v[188:191], v[8:11]
	s_setprio 0
	s_setprio 1
	v_mfma_f32_16x16x32_bf16 v[52:55], v[104:107], v[152:155], v[52:55]
	v_mfma_f32_16x16x32_bf16 v[48:51], v[120:123], v[152:155], v[48:51]
	v_mfma_f32_16x16x32_bf16 v[36:39], v[104:107], v[168:171], v[36:39]
	v_mfma_f32_16x16x32_bf16 v[32:35], v[120:123], v[168:171], v[32:35]
	v_mfma_f32_16x16x32_bf16 v[20:23], v[104:107], v[176:179], v[20:23]
	v_mfma_f32_16x16x32_bf16 v[16:19], v[120:123], v[176:179], v[16:19]
	v_mfma_f32_16x16x32_bf16 v[4:7], v[104:107], v[184:187], v[4:7]
	v_mfma_f32_16x16x32_bf16 v[0:3], v[120:123], v[184:187], v[0:3]
	v_mfma_f32_16x16x32_bf16 v[52:55], v[108:111], v[164:167], v[52:55]
	v_mfma_f32_16x16x32_bf16 v[48:51], v[132:135], v[164:167], v[48:51]
	v_mfma_f32_16x16x32_bf16 v[36:39], v[108:111], v[172:175], v[36:39]
	v_mfma_f32_16x16x32_bf16 v[32:35], v[132:135], v[172:175], v[32:35]
	v_mfma_f32_16x16x32_bf16 v[20:23], v[108:111], v[180:183], v[20:23]
	v_mfma_f32_16x16x32_bf16 v[16:19], v[132:135], v[180:183], v[16:19]
	v_mfma_f32_16x16x32_bf16 v[4:7], v[108:111], v[188:191], v[4:7]
	v_mfma_f32_16x16x32_bf16 v[0:3], v[132:135], v[188:191], v[0:3]
	s_setprio 0
	s_barrier
	s_add_i32 s48, 0, 0x18000
	s_add_i32 s49, 0, 0x1c000
	v_add_u32_e32 v92, s48, v234
	v_add_u32_e32 v132, s49, v234
	ds_read_b128 v[64:67], v92
	ds_read_b128 v[68:71], v92 offset:1024
	ds_read_b128 v[80:83], v92 offset:2048
	ds_read_b128 v[92:95], v92 offset:3072
	ds_read_b128 v[104:107], v132
	ds_read_b128 v[108:111], v132 offset:1024
	ds_read_b128 v[120:123], v132 offset:2048
	ds_read_b128 v[132:135], v132 offset:3072
	s_add_u32 s28, s40, 0x60000
	s_addc_u32 s29, s41, 0
	s_mov_b32 m0, s63
	v_lshl_add_u64 v[216:217], s[28:29], 0, v[202:203]
	ds_read_b128 v[152:155], v235 offset:32768
	ds_read_b128 v[164:167], v235 offset:33792
	ds_read_b128 v[168:171], v235 offset:34816
	ds_read_b128 v[172:175], v235 offset:35840
	ds_read_b128 v[176:179], v235 offset:36864
	ds_read_b128 v[180:183], v235 offset:37888
	ds_read_b128 v[184:187], v235 offset:38912
	ds_read_b128 v[188:191], v235 offset:39936
	global_load_lds_dwordx4 v[216:217], off
	v_lshl_add_u64 v[216:217], s[28:29], 0, v[200:201]
	s_mov_b32 m0, s64
	s_nop 0
	global_load_lds_dwordx4 v[216:217], off
	s_waitcnt vmcnt(8)
	s_waitcnt lgkmcnt(0)
	s_barrier
	s_setprio 1
	s_waitcnt lgkmcnt(0)
	v_mfma_f32_16x16x32_bf16 v[160:163], v[64:67], v[152:155], v[160:163]
	v_mfma_f32_16x16x32_bf16 v[156:159], v[80:83], v[152:155], v[156:159]
	v_mfma_f32_16x16x32_bf16 v[140:143], v[64:67], v[168:171], v[140:143]
	v_mfma_f32_16x16x32_bf16 v[136:139], v[80:83], v[168:171], v[136:139]
	v_mfma_f32_16x16x32_bf16 v[116:119], v[64:67], v[176:179], v[116:119]
	v_mfma_f32_16x16x32_bf16 v[112:115], v[80:83], v[176:179], v[112:115]
	v_mfma_f32_16x16x32_bf16 v[88:91], v[64:67], v[184:187], v[88:91]
	v_mfma_f32_16x16x32_bf16 v[84:87], v[80:83], v[184:187], v[84:87]
	v_mfma_f32_16x16x32_bf16 v[160:163], v[68:71], v[164:167], v[160:163]
	v_mfma_f32_16x16x32_bf16 v[156:159], v[92:95], v[164:167], v[156:159]
	v_mfma_f32_16x16x32_bf16 v[140:143], v[68:71], v[172:175], v[140:143]
	v_mfma_f32_16x16x32_bf16 v[136:139], v[92:95], v[172:175], v[136:139]
	v_mfma_f32_16x16x32_bf16 v[116:119], v[68:71], v[180:183], v[116:119]
	v_mfma_f32_16x16x32_bf16 v[112:115], v[92:95], v[180:183], v[112:115]
	v_mfma_f32_16x16x32_bf16 v[88:91], v[68:71], v[188:191], v[88:91]
	v_mfma_f32_16x16x32_bf16 v[84:87], v[92:95], v[188:191], v[84:87]
	s_setprio 0
	s_setprio 1
	v_mfma_f32_16x16x32_bf16 v[148:151], v[104:107], v[152:155], v[148:151]
	v_mfma_f32_16x16x32_bf16 v[144:147], v[120:123], v[152:155], v[144:147]
	v_mfma_f32_16x16x32_bf16 v[128:131], v[104:107], v[168:171], v[128:131]
	v_mfma_f32_16x16x32_bf16 v[124:127], v[120:123], v[168:171], v[124:127]
	v_mfma_f32_16x16x32_bf16 v[100:103], v[104:107], v[176:179], v[100:103]
	v_mfma_f32_16x16x32_bf16 v[96:99], v[120:123], v[176:179], v[96:99]
	v_mfma_f32_16x16x32_bf16 v[76:79], v[104:107], v[184:187], v[76:79]
	v_mfma_f32_16x16x32_bf16 v[72:75], v[120:123], v[184:187], v[72:75]
	v_mfma_f32_16x16x32_bf16 v[148:151], v[108:111], v[164:167], v[148:151]
	v_mfma_f32_16x16x32_bf16 v[144:147], v[132:135], v[164:167], v[144:147]
	v_mfma_f32_16x16x32_bf16 v[128:131], v[108:111], v[172:175], v[128:131]
	v_mfma_f32_16x16x32_bf16 v[124:127], v[132:135], v[172:175], v[124:127]
	v_mfma_f32_16x16x32_bf16 v[100:103], v[108:111], v[180:183], v[100:103]
	v_mfma_f32_16x16x32_bf16 v[96:99], v[132:135], v[180:183], v[96:99]
	v_mfma_f32_16x16x32_bf16 v[76:79], v[108:111], v[188:191], v[76:79]
	v_mfma_f32_16x16x32_bf16 v[72:75], v[132:135], v[188:191], v[72:75]
	s_setprio 0
	s_barrier
; #define PG8_STAGE(bufoff, gbase, voff) do { _Pragma("unroll") for (int _i = 0; _i < 2; ++_i) \
;         __builtin_amdgcn_global_load_lds((const unsigned*)((const char*)(gbase) + (voff)[_i]), (PG8_LAS unsigned*)(lds + (bufoff) + ldsw + _i * 8192), 16, 0, 0); } while (0)
; #define PG8_LDA(dst, b, h) do { _Pragma("unroll") for (int m = 0; m < 4; ++m) _Pragma("unroll") for (int k = 0; k < 2; ++k) dst[m][k] = *(const PG8_LAS bf16x8*)(lds + PG8_SA(b, h) + aoff + m * 2048 + k * 1024); } while (0)
; #define PG8_MMA(ai, bj, At, Bt) do { __builtin_amdgcn_s_setprio(1); _Pragma("unroll") for (int m = 0; m < 4; ++m) _Pragma("unroll") for (int n = 0; n < 2; ++n) _Pragma("unroll") for (int k = 0; k < 2; ++k) \
;         acc[ai][bj][m][n] = __builtin_amdgcn_mfma_f32_16x16x32_bf16(Bt[n][k], At[m][k], acc[ai][bj][m][n], 0, 0, 0); __builtin_amdgcn_s_setprio(0); } while (0)
; #define PG8_WAIT_V(n) asm volatile("s_waitcnt vmcnt(" #n ")" ::: "memory")
; #define PG8_WAIT_L(n) asm volatile("s_waitcnt lgkmcnt(" #n ")" ::: "memory")
; #define PG8_BAR __builtin_amdgcn_s_barrier()
; #define PG8_SCHED __builtin_amdgcn_sched_barrier(0)
;     ...
;         for (int t = 0; t < nt; t += 2) {
;     ...
;             PG8_LDA(At, 1, 1); PG8_STAGE(PG8_SB(1, 0), b3, voffB); PG8_STAGE(PG8_SB(1, 1), b3 + hstepB, voffB); PG8_STAGE(PG8_SA(1, 0), a3, voffA);
;             PG8_WAIT_V(8); PG8_WAIT_L(0); PG8_BAR; PG8_MMA(1, 0, At, B0); PG8_MMA(1, 1, At, B1); PG8_BAR; PG8_SCHED;
	s_add_i32 s28, s48, s58
	v_lshl_add_u64 v[208:209], v[208:209], 0, s[22:23]
	s_mov_b32 m0, s28
	ds_read_b128 v[152:155], v235 offset:49152
	ds_read_b128 v[164:167], v235 offset:50176
	ds_read_b128 v[168:171], v235 offset:51200
	ds_read_b128 v[172:175], v235 offset:52224
	ds_read_b128 v[176:179], v235 offset:53248
	ds_read_b128 v[180:183], v235 offset:54272
	ds_read_b128 v[184:187], v235 offset:55296
	ds_read_b128 v[188:191], v235 offset:56320
	global_load_lds_dwordx4 v[208:209], off
	s_add_i32 m0, s28, 0x2000
	s_add_u32 s28, s34, 0x40080
	v_lshl_add_u64 v[208:209], v[210:211], 0, s[22:23]
	s_addc_u32 s29, s35, 0
	s_add_i32 s34, s49, s58
	global_load_lds_dwordx4 v[208:209], off
	v_lshl_add_u64 v[208:209], s[28:29], 0, v[192:193]
	s_mov_b32 m0, s34
	s_nop 0
	global_load_lds_dwordx4 v[208:209], off
	v_lshl_add_u64 v[208:209], s[28:29], 0, v[198:199]
	s_add_i32 m0, s34, 0x2000
	s_nop 0
	global_load_lds_dwordx4 v[208:209], off
	v_lshl_add_u64 v[208:209], v[212:213], 0, s[22:23]
	s_mov_b32 m0, s67
	s_nop 0
	global_load_lds_dwordx4 v[208:209], off
	v_lshl_add_u64 v[208:209], v[214:215], 0, s[22:23]
	s_mov_b32 m0, s68
	s_nop 0
	global_load_lds_dwordx4 v[208:209], off
	s_waitcnt vmcnt(8)
	s_waitcnt lgkmcnt(0)
	s_barrier
	s_setprio 1
	s_waitcnt lgkmcnt(0)
	v_mfma_f32_16x16x32_bf16 v[60:63], v[64:67], v[152:155], v[60:63]
	v_mfma_f32_16x16x32_bf16 v[56:59], v[80:83], v[152:155], v[56:59]
	v_mfma_f32_16x16x32_bf16 v[44:47], v[64:67], v[168:171], v[44:47]
	v_mfma_f32_16x16x32_bf16 v[40:43], v[80:83], v[168:171], v[40:43]
	v_mfma_f32_16x16x32_bf16 v[28:31], v[64:67], v[176:179], v[28:31]
	v_mfma_f32_16x16x32_bf16 v[24:27], v[80:83], v[176:179], v[24:27]
	v_mfma_f32_16x16x32_bf16 v[12:15], v[64:67], v[184:187], v[12:15]
	v_mfma_f32_16x16x32_bf16 v[8:11], v[80:83], v[184:187], v[8:11]
	v_mfma_f32_16x16x32_bf16 v[60:63], v[68:71], v[164:167], v[60:63]
	v_mfma_f32_16x16x32_bf16 v[56:59], v[92:95], v[164:167], v[56:59]
	v_mfma_f32_16x16x32_bf16 v[44:47], v[68:71], v[172:175], v[44:47]
	v_mfma_f32_16x16x32_bf16 v[40:43], v[92:95], v[172:175], v[40:43]
	v_mfma_f32_16x16x32_bf16 v[28:31], v[68:71], v[180:183], v[28:31]
	v_mfma_f32_16x16x32_bf16 v[24:27], v[92:95], v[180:183], v[24:27]
	v_mfma_f32_16x16x32_bf16 v[12:15], v[68:71], v[188:191], v[12:15]
	v_mfma_f32_16x16x32_bf16 v[8:11], v[92:95], v[188:191], v[8:11]
	s_setprio 0
	s_setprio 1
	v_mfma_f32_16x16x32_bf16 v[52:55], v[104:107], v[152:155], v[52:55]
	v_mfma_f32_16x16x32_bf16 v[48:51], v[120:123], v[152:155], v[48:51]
	v_mfma_f32_16x16x32_bf16 v[36:39], v[104:107], v[168:171], v[36:39]
	v_mfma_f32_16x16x32_bf16 v[32:35], v[120:123], v[168:171], v[32:35]
	v_mfma_f32_16x16x32_bf16 v[20:23], v[104:107], v[176:179], v[20:23]
	v_mfma_f32_16x16x32_bf16 v[16:19], v[120:123], v[176:179], v[16:19]
	v_mfma_f32_16x16x32_bf16 v[4:7], v[104:107], v[184:187], v[4:7]
	v_mfma_f32_16x16x32_bf16 v[0:3], v[120:123], v[184:187], v[0:3]
	v_mfma_f32_16x16x32_bf16 v[52:55], v[108:111], v[164:167], v[52:55]
	v_mfma_f32_16x16x32_bf16 v[48:51], v[132:135], v[164:167], v[48:51]
	v_mfma_f32_16x16x32_bf16 v[36:39], v[108:111], v[172:175], v[36:39]
	v_mfma_f32_16x16x32_bf16 v[32:35], v[132:135], v[172:175], v[32:35]
	v_mfma_f32_16x16x32_bf16 v[20:23], v[108:111], v[180:183], v[20:23]
	v_mfma_f32_16x16x32_bf16 v[16:19], v[132:135], v[180:183], v[16:19]
	v_mfma_f32_16x16x32_bf16 v[4:7], v[108:111], v[188:191], v[4:7]
	v_mfma_f32_16x16x32_bf16 v[0:3], v[132:135], v[188:191], v[0:3]
	s_setprio 0
	s_barrier
	s_add_i32 s76, s76, 2
	s_add_u32 s74, s74, 0x100
	s_addc_u32 s75, s75, 0
	s_cmp_gt_u32 s76, 13
	s_mov_b64 s[28:29], s[6:7]
	s_cbranch_scc0 .LBB0_1083
	s_mov_b32 s98, 1
	s_and_b64 vcc, exec, s[36:37]
	s_cbranch_vccz .LBB0_1086
	s_barrier

; #define PG8_STAGE(bufoff, gbase, voff) do { _Pragma("unroll") for (int _i = 0; _i < 2; ++_i) \
;         __builtin_amdgcn_global_load_lds((const unsigned*)((const char*)(gbase) + (voff)[_i]), (PG8_LAS unsigned*)(lds + (bufoff) + ldsw + _i * 8192), 16, 0, 0); } while (0)
; #define PG8_WAIT_V(n) asm volatile("s_waitcnt vmcnt(" #n ")" ::: "memory")
; #define PG8_BAR __builtin_amdgcn_s_barrier()
;     ...
;     for (int i = 0; i < 2; ++i) { int R, C; stage_rc(tid * 16 + i * 8192, R, C); const int Rb = Epi::PERM ? ((R & ~31) + perm32(R & 31)) : R;
;         voffA[i] = (unsigned)(R * lda_ + C) * 2u; voffB[i] = (unsigned)(Rb * K + C) * 2u; }
;     const size_t kstep = (size_t)(BK * 2);
;     const size_t hstepA = (size_t)HALF * lda_ * 2, hstepB = (size_t)HALF * K * 2;
;     const size_t tstepA = 2 * hstepA, tstepB = 2 * hstepB;
;     const unsigned ldsw = (unsigned)wid * 1024u;
;     const int aoff = lds_byte(wr * 64 + fr, fq * 8), boff = lds_byte(wc * 32 + fr, fq * 8);
;     ...
;         PG8_STAGE(PG8_SB(1, 0), cB + kstep, voffB); PG8_STAGE(PG8_SA(1, 0), cA + kstep, voffA); PG8_STAGE(PG8_SB(1, 1), cB + hstepB + kstep, voffB);
;         PG8_WAIT_V(6); PG8_BAR;
.LBB0_1242:
	s_add_u32 s16, s6, 0x2e00000
	s_addc_u32 s17, s7, 0
	s_add_u32 s6, s6, 0x4800000
	s_addc_u32 s7, s7, 0
	s_lshl_b32 s51, s0, 6
	s_lshl_b32 s21, s0, 13
	s_lshl_b32 s0, s1, 5
	s_mov_b64 s[18:19], 0x80
	s_and_b32 s52, s0, 0x60
	s_add_i32 m0, s39, 0x18000
	v_lshl_add_u64 v[6:7], v[6:7], 0, s[18:19]
	s_lshl_b32 s22, s52, 7
	s_waitcnt vmcnt(2)
	s_barrier
	global_load_lds_dwordx4 v[6:7], off
	v_lshl_add_u64 v[4:5], v[4:5], 0, s[18:19]
	s_add_i32 m0, s39, 0x1a000
	s_add_i32 s53, s39, 0x8000
	s_add_i32 s54, s39, 0xa000
	global_load_lds_dwordx4 v[4:5], off
	v_lshl_add_u64 v[0:1], v[0:1], 0, s[18:19]
	s_mov_b32 m0, s53
	s_add_u32 s0, s34, 0x40080
	global_load_lds_dwordx4 v[0:1], off
	v_lshl_add_u64 v[0:1], v[2:3], 0, s[18:19]
	s_mov_b32 m0, s54
	s_addc_u32 s1, s35, 0
	global_load_lds_dwordx4 v[0:1], off
	s_add_i32 m0, s39, 0x1c000
	v_lshl_add_u64 v[0:1], s[0:1], 0, v[178:179]
	global_load_lds_dwordx4 v[0:1], off
	v_lshl_add_u64 v[0:1], s[0:1], 0, v[182:183]
	s_add_i32 m0, s39, 0x1e000
	s_movk_i32 s0, 0x3c0
	global_load_lds_dwordx4 v[0:1], off
	v_and_b32_e32 v0, 48, v8
	v_lshlrev_b32_e32 v1, 6, v8
	v_and_or_b32 v0, v1, s0, v0
	v_lshlrev_b32_e32 v1, 2, v8
	v_and_b32_e32 v1, 32, v1
	v_bitop3_b32 v2, v0, s21, v1 bitop3:0xde
	v_bitop3_b32 v202, s22, v0, v1 bitop3:0xf6
	v_lshlrev_b32_e32 v0, 14, v9
	v_and_b32_e32 v0, 0xffff8000, v0
	v_lshl_add_u32 v0, v10, 11, v0
	v_and_b32_e32 v1, 1, v9
	v_lshl_or_b32 v0, v1, 6, v0
	v_lshl_add_u32 v184, v11, 1, v0
	v_lshlrev_b32_e32 v0, 14, v12
	v_and_b32_e32 v0, 0xffff8000, v0
	s_waitcnt vmcnt(6)
	s_cmpk_lt_u32 s20, 0x100
	v_lshl_add_u32 v0, v13, 11, v0
	v_and_b32_e32 v1, 1, v12
	s_cselect_b64 s[20:21], -1, 0
	v_lshl_or_b32 v0, v1, 6, v0
	s_add_i32 s55, 0, 0x10000
	s_add_i32 s56, 0, 0x14000
	v_mov_b32_e32 v185, v179
	v_lshl_add_u32 v186, v14, 1, v0
	v_mov_b32_e32 v187, v179
	v_mov_b64_e32 v[188:189], 0x400
	v_mov_b64_e32 v[190:191], 0x3ff
	v_add_u32_e32 v203, s55, v202
	v_add_u32_e32 v204, s56, v202
	v_add_u32_e32 v205, 0, v2
	s_barrier
	s_mov_b32 s98, 0
	s_branch .LBB0_1245
.Lfi_p5_a:
	s_waitcnt vmcnt(56)
	s_branch .Lfi_p5_aj

; #define PG8_STAGE(bufoff, gbase, voff) do { _Pragma("unroll") for (int _i = 0; _i < 2; ++_i) \
;         __builtin_amdgcn_global_load_lds((const unsigned*)((const char*)(gbase) + (voff)[_i]), (PG8_LAS unsigned*)(lds + (bufoff) + ldsw + _i * 8192), 16, 0, 0); } while (0)
; #define PG8_LDA(dst, b, h) do { _Pragma("unroll") for (int m = 0; m < 4; ++m) _Pragma("unroll") for (int k = 0; k < 2; ++k) dst[m][k] = *(const PG8_LAS bf16x8*)(lds + PG8_SA(b, h) + aoff + m * 2048 + k * 1024); } while (0)
; #define PG8_LDB(dst, b, h) do { _Pragma("unroll") for (int n = 0; n < 2; ++n) _Pragma("unroll") for (int k = 0; k < 2; ++k) dst[n][k] = *(const PG8_LAS bf16x8*)(lds + PG8_SB(b, h) + boff + n * 2048 + k * 1024); } while (0)
; #define PG8_MMA(ai, bj, At, Bt) do { __builtin_amdgcn_s_setprio(1); _Pragma("unroll") for (int m = 0; m < 4; ++m) _Pragma("unroll") for (int n = 0; n < 2; ++n) _Pragma("unroll") for (int k = 0; k < 2; ++k) \
;         acc[ai][bj][m][n] = __builtin_amdgcn_mfma_f32_16x16x32_bf16(Bt[n][k], At[m][k], acc[ai][bj][m][n], 0, 0, 0); __builtin_amdgcn_s_setprio(0); } while (0)
; #define PG8_WAIT_V(n) asm volatile("s_waitcnt vmcnt(" #n ")" ::: "memory")
; #define PG8_WAIT_L(n) asm volatile("s_waitcnt lgkmcnt(" #n ")" ::: "memory")
; #define PG8_BAR __builtin_amdgcn_s_barrier()
; #define PG8_SCHED __builtin_amdgcn_sched_barrier(0)
;     ...
;             const char* a2 = last ? nA : cA + (size_t)(t + 2) * kstep; const char* b2 = last ? nB : cB + (size_t)(t + 2) * kstep;
;             const char* a3 = a2 + kstep; const char* b3 = b2 + kstep;
;             if (last && has_next) S.a_ready(nxt);
;             if constexpr (SP2) {
;             PG8_LDB(B0, 0, 0); PG8_LDB(B1, 0, 1); PG8_SCHED; PG8_LDA(At, 0, 0); PG8_STAGE(PG8_SA(1, 1), a1 + hstepA, voffA);
;             PG8_WAIT_V(8); PG8_WAIT_L(0); PG8_BAR; PG8_MMA(0, 0, At, B0); PG8_MMA(0, 1, At, B1); PG8_BAR; PG8_SCHED;
;             PG8_LDA(At, 0, 1); PG8_STAGE(PG8_SB(0, 0), b2, voffB); PG8_STAGE(PG8_SB(0, 1), b2 + hstepB, voffB); PG8_STAGE(PG8_SA(0, 0), a2, voffA);
.LBB0_1252:
	ds_read_b128 v[128:131], v203
	ds_read_b128 v[132:135], v203 offset:1024
	ds_read_b128 v[136:139], v203 offset:2048
	ds_read_b128 v[140:143], v203 offset:3072
	ds_read_b128 v[144:147], v204
	ds_read_b128 v[148:151], v204 offset:1024
	ds_read_b128 v[152:155], v204 offset:2048
	ds_read_b128 v[156:159], v204 offset:3072
	s_add_u32 s34, s28, 0xfffc0080
	s_addc_u32 s35, s29, -1
	s_cmp_eq_u32 s61, 12
	s_cselect_b32 s41, s25, s35
	s_cselect_b32 s40, s57, s34
	s_cselect_b32 s35, s23, s60
	s_cselect_b32 s34, s58, s59
	v_lshl_add_u64 v[200:201], s[28:29], 0, v[184:185]
	s_add_i32 m0, s39, 0xc000
	ds_read_b128 v[160:163], v205
	ds_read_b128 v[164:167], v205 offset:1024
	ds_read_b128 v[168:171], v205 offset:2048
	ds_read_b128 v[172:175], v205 offset:3072
	ds_read_b128 v[192:195], v205 offset:4096
	ds_read_b128 v[196:199], v205 offset:5120
	ds_read_b128 v[206:209], v205 offset:6144
	ds_read_b128 v[210:213], v205 offset:7168
	global_load_lds_dwordx4 v[200:201], off
	v_lshl_add_u64 v[200:201], s[28:29], 0, v[186:187]
	s_add_i32 m0, s39, 0xe000
	s_nop 0
	global_load_lds_dwordx4 v[200:201], off
	s_cmp_lg_u32 s98, 0
	s_cbranch_scc1 .Lfi_p5_a
	s_waitcnt vmcnt(8)
.Lfi_p5_aj:
	s_waitcnt lgkmcnt(0)
	s_barrier
	s_setprio 1
	s_waitcnt lgkmcnt(0)
	v_mfma_f32_16x16x32_bf16 v[124:127], v[128:131], v[160:163], v[124:127]
	v_mfma_f32_16x16x32_bf16 v[120:123], v[136:139], v[160:163], v[120:123]
	v_mfma_f32_16x16x32_bf16 v[108:111], v[128:131], v[168:171], v[108:111]
	v_mfma_f32_16x16x32_bf16 v[104:107], v[136:139], v[168:171], v[104:107]
	v_mfma_f32_16x16x32_bf16 v[92:95], v[128:131], v[192:195], v[92:95]
	v_mfma_f32_16x16x32_bf16 v[88:91], v[136:139], v[192:195], v[88:91]
	v_mfma_f32_16x16x32_bf16 v[76:79], v[128:131], v[206:209], v[76:79]
	v_mfma_f32_16x16x32_bf16 v[72:75], v[136:139], v[206:209], v[72:75]
	v_mfma_f32_16x16x32_bf16 v[124:127], v[132:135], v[164:167], v[124:127]
	v_mfma_f32_16x16x32_bf16 v[120:123], v[140:143], v[164:167], v[120:123]
	v_mfma_f32_16x16x32_bf16 v[108:111], v[132:135], v[172:175], v[108:111]
	v_mfma_f32_16x16x32_bf16 v[104:107], v[140:143], v[172:175], v[104:107]
	v_mfma_f32_16x16x32_bf16 v[92:95], v[132:135], v[196:199], v[92:95]
	v_mfma_f32_16x16x32_bf16 v[88:91], v[140:143], v[196:199], v[88:91]
	v_mfma_f32_16x16x32_bf16 v[76:79], v[132:135], v[210:213], v[76:79]
	v_mfma_f32_16x16x32_bf16 v[72:75], v[140:143], v[210:213], v[72:75]
	s_setprio 0
	s_setprio 1
	v_mfma_f32_16x16x32_bf16 v[116:119], v[144:147], v[160:163], v[116:119]
	v_mfma_f32_16x16x32_bf16 v[112:115], v[152:155], v[160:163], v[112:115]
	v_mfma_f32_16x16x32_bf16 v[100:103], v[144:147], v[168:171], v[100:103]
	v_mfma_f32_16x16x32_bf16 v[96:99], v[152:155], v[168:171], v[96:99]
	v_mfma_f32_16x16x32_bf16 v[84:87], v[144:147], v[192:195], v[84:87]
	v_mfma_f32_16x16x32_bf16 v[80:83], v[152:155], v[192:195], v[80:83]
	v_mfma_f32_16x16x32_bf16 v[68:71], v[144:147], v[206:209], v[68:71]
	v_mfma_f32_16x16x32_bf16 v[64:67], v[152:155], v[206:209], v[64:67]
	v_mfma_f32_16x16x32_bf16 v[116:119], v[148:151], v[164:167], v[116:119]
	v_mfma_f32_16x16x32_bf16 v[112:115], v[156:159], v[164:167], v[112:115]
	v_mfma_f32_16x16x32_bf16 v[100:103], v[148:151], v[172:175], v[100:103]
	v_mfma_f32_16x16x32_bf16 v[96:99], v[156:159], v[172:175], v[96:99]
	v_mfma_f32_16x16x32_bf16 v[84:87], v[148:151], v[196:199], v[84:87]
	v_mfma_f32_16x16x32_bf16 v[80:83], v[156:159], v[196:199], v[80:83]
	v_mfma_f32_16x16x32_bf16 v[68:71], v[148:151], v[210:213], v[68:71]
	v_mfma_f32_16x16x32_bf16 v[64:67], v[156:159], v[210:213], v[64:67]
	s_setprio 0
	s_barrier
	s_add_i32 s48, s55, s43
	v_lshl_add_u64 v[200:201], s[34:35], 0, v[178:179]
	s_mov_b32 m0, s48
	ds_read_b128 v[160:163], v205 offset:16384
	ds_read_b128 v[164:167], v205 offset:17408
	ds_read_b128 v[168:171], v205 offset:18432
	ds_read_b128 v[172:175], v205 offset:19456
	ds_read_b128 v[192:195], v205 offset:20480
	ds_read_b128 v[196:199], v205 offset:21504
	ds_read_b128 v[206:209], v205 offset:22528
	ds_read_b128 v[210:213], v205 offset:23552
	global_load_lds_dwordx4 v[200:201], off
	s_add_i32 m0, s48, 0x2000
	s_add_u32 s48, s34, 0x40000
	v_lshl_add_u64 v[214:215], s[34:35], 0, v[182:183]
	s_addc_u32 s49, s35, 0
	s_add_i32 s62, s56, s43
	global_load_lds_dwordx4 v[214:215], off
	v_lshl_add_u64 v[216:217], s[48:49], 0, v[178:179]
	s_mov_b32 m0, s62
	v_lshl_add_u64 v[218:219], s[40:41], 0, v[180:181]
	global_load_lds_dwordx4 v[216:217], off
	v_lshl_add_u64 v[216:217], s[48:49], 0, v[182:183]
	s_add_i32 m0, s62, 0x2000
	s_nop 0
	global_load_lds_dwordx4 v[216:217], off
	v_lshl_add_u64 v[216:217], s[40:41], 0, v[176:177]
	s_mov_b32 m0, s39
	s_nop 0
	global_load_lds_dwordx4 v[216:217], off
	s_mov_b32 m0, s45
	s_nop 0
	global_load_lds_dwordx4 v[218:219], off
	s_cmp_lg_u32 s98, 0
	s_cbranch_scc1 .Lfi_p5_b
	s_waitcnt vmcnt(8)
; #define PG8_STAGE(bufoff, gbase, voff) do { _Pragma("unroll") for (int _i = 0; _i < 2; ++_i) \
;         __builtin_amdgcn_global_load_lds((const unsigned*)((const char*)(gbase) + (voff)[_i]), (PG8_LAS unsigned*)(lds + (bufoff) + ldsw + _i * 8192), 16, 0, 0); } while (0)
; #define PG8_LDA(dst, b, h) do { _Pragma("unroll") for (int m = 0; m < 4; ++m) _Pragma("unroll") for (int k = 0; k < 2; ++k) dst[m][k] = *(const PG8_LAS bf16x8*)(lds + PG8_SA(b, h) + aoff + m * 2048 + k * 1024); } while (0)
; #define PG8_LDB(dst, b, h) do { _Pragma("unroll") for (int n = 0; n < 2; ++n) _Pragma("unroll") for (int k = 0; k < 2; ++k) dst[n][k] = *(const PG8_LAS bf16x8*)(lds + PG8_SB(b, h) + boff + n * 2048 + k * 1024); } while (0)
; #define PG8_MMA(ai, bj, At, Bt) do { __builtin_amdgcn_s_setprio(1); _Pragma("unroll") for (int m = 0; m < 4; ++m) _Pragma("unroll") for (int n = 0; n < 2; ++n) _Pragma("unroll") for (int k = 0; k < 2; ++k) \
;         acc[ai][bj][m][n] = __builtin_amdgcn_mfma_f32_16x16x32_bf16(Bt[n][k], At[m][k], acc[ai][bj][m][n], 0, 0, 0); __builtin_amdgcn_s_setprio(0); } while (0)
; #define PG8_WAIT_V(n) asm volatile("s_waitcnt vmcnt(" #n ")" ::: "memory")
; #define PG8_WAIT_L(n) asm volatile("s_waitcnt lgkmcnt(" #n ")" ::: "memory")
; #define PG8_BAR __builtin_amdgcn_s_barrier()
; #define PG8_SCHED __builtin_amdgcn_sched_barrier(0)
;     ...
;             PG8_WAIT_V(8); PG8_WAIT_L(0); PG8_BAR; PG8_MMA(1, 0, At, B0); PG8_MMA(1, 1, At, B1); PG8_BAR; PG8_SCHED;
;             PG8_LDB(B0, 1, 0); PG8_LDB(B1, 1, 1); PG8_SCHED; PG8_LDA(At, 1, 0); PG8_STAGE(PG8_SA(0, 1), a2 + hstepA, voffA);
;             PG8_WAIT_V(8); PG8_WAIT_L(0); PG8_BAR; PG8_MMA(0, 0, At, B0); PG8_MMA(0, 1, At, B1); PG8_BAR; PG8_SCHED;
.Lfi_p5_bj:
	s_mov_b32 s98, 0
	s_waitcnt lgkmcnt(0)
	s_barrier
	s_setprio 1
	s_waitcnt lgkmcnt(0)
	v_mfma_f32_16x16x32_bf16 v[60:63], v[128:131], v[160:163], v[60:63]
	v_mfma_f32_16x16x32_bf16 v[56:59], v[136:139], v[160:163], v[56:59]
	v_mfma_f32_16x16x32_bf16 v[44:47], v[128:131], v[168:171], v[44:47]
	v_mfma_f32_16x16x32_bf16 v[40:43], v[136:139], v[168:171], v[40:43]
	v_mfma_f32_16x16x32_bf16 v[28:31], v[128:131], v[192:195], v[28:31]
	v_mfma_f32_16x16x32_bf16 v[24:27], v[136:139], v[192:195], v[24:27]
	v_mfma_f32_16x16x32_bf16 v[12:15], v[128:131], v[206:209], v[12:15]
	v_mfma_f32_16x16x32_bf16 v[8:11], v[136:139], v[206:209], v[8:11]
	v_mfma_f32_16x16x32_bf16 v[60:63], v[132:135], v[164:167], v[60:63]
	v_mfma_f32_16x16x32_bf16 v[56:59], v[140:143], v[164:167], v[56:59]
	v_mfma_f32_16x16x32_bf16 v[44:47], v[132:135], v[172:175], v[44:47]
	v_mfma_f32_16x16x32_bf16 v[40:43], v[140:143], v[172:175], v[40:43]
	v_mfma_f32_16x16x32_bf16 v[28:31], v[132:135], v[196:199], v[28:31]
	v_mfma_f32_16x16x32_bf16 v[24:27], v[140:143], v[196:199], v[24:27]
	v_mfma_f32_16x16x32_bf16 v[12:15], v[132:135], v[210:213], v[12:15]
	v_mfma_f32_16x16x32_bf16 v[8:11], v[140:143], v[210:213], v[8:11]
	s_setprio 0
	s_setprio 1
	v_mfma_f32_16x16x32_bf16 v[52:55], v[144:147], v[160:163], v[52:55]
	v_mfma_f32_16x16x32_bf16 v[48:51], v[152:155], v[160:163], v[48:51]
	v_mfma_f32_16x16x32_bf16 v[36:39], v[144:147], v[168:171], v[36:39]
	v_mfma_f32_16x16x32_bf16 v[32:35], v[152:155], v[168:171], v[32:35]
	v_mfma_f32_16x16x32_bf16 v[20:23], v[144:147], v[192:195], v[20:23]
	v_mfma_f32_16x16x32_bf16 v[16:19], v[152:155], v[192:195], v[16:19]
	v_mfma_f32_16x16x32_bf16 v[4:7], v[144:147], v[206:209], v[4:7]
	v_mfma_f32_16x16x32_bf16 v[0:3], v[152:155], v[206:209], v[0:3]
	v_mfma_f32_16x16x32_bf16 v[52:55], v[148:151], v[164:167], v[52:55]
	v_mfma_f32_16x16x32_bf16 v[48:51], v[156:159], v[164:167], v[48:51]
	v_mfma_f32_16x16x32_bf16 v[36:39], v[148:151], v[172:175], v[36:39]
	v_mfma_f32_16x16x32_bf16 v[32:35], v[156:159], v[172:175], v[32:35]
	v_mfma_f32_16x16x32_bf16 v[20:23], v[148:151], v[196:199], v[20:23]
	v_mfma_f32_16x16x32_bf16 v[16:19], v[156:159], v[196:199], v[16:19]
	v_mfma_f32_16x16x32_bf16 v[4:7], v[148:151], v[210:213], v[4:7]
	v_mfma_f32_16x16x32_bf16 v[0:3], v[156:159], v[210:213], v[0:3]
	s_setprio 0
	s_barrier
	s_add_i32 s48, 0, 0x18000
	s_add_i32 s49, 0, 0x1c000
	v_add_u32_e32 v140, s48, v202
	v_add_u32_e32 v156, s49, v202
	ds_read_b128 v[128:131], v140
	ds_read_b128 v[132:135], v140 offset:1024
	ds_read_b128 v[136:139], v140 offset:2048
	ds_read_b128 v[140:143], v140 offset:3072
	ds_read_b128 v[144:147], v156
	ds_read_b128 v[148:151], v156 offset:1024
	ds_read_b128 v[152:155], v156 offset:2048
	ds_read_b128 v[156:159], v156 offset:3072
	s_add_u32 s40, s40, 0x40000
	s_addc_u32 s41, s41, 0
	s_mov_b32 m0, s46
	v_lshl_add_u64 v[220:221], s[40:41], 0, v[176:177]
	ds_read_b128 v[160:163], v205 offset:32768
	ds_read_b128 v[164:167], v205 offset:33792
	ds_read_b128 v[168:171], v205 offset:34816
	ds_read_b128 v[172:175], v205 offset:35840
	ds_read_b128 v[192:195], v205 offset:36864
	ds_read_b128 v[196:199], v205 offset:37888
	ds_read_b128 v[206:209], v205 offset:38912
	ds_read_b128 v[210:213], v205 offset:39936
	global_load_lds_dwordx4 v[220:221], off
	v_lshl_add_u64 v[220:221], s[40:41], 0, v[180:181]
	s_mov_b32 m0, s47
	s_nop 0
	global_load_lds_dwordx4 v[220:221], off
	s_waitcnt vmcnt(8)
	s_waitcnt lgkmcnt(0)
	s_barrier
	s_setprio 1
	s_waitcnt lgkmcnt(0)
	v_mfma_f32_16x16x32_bf16 v[124:127], v[128:131], v[160:163], v[124:127]
	v_mfma_f32_16x16x32_bf16 v[120:123], v[136:139], v[160:163], v[120:123]
	v_mfma_f32_16x16x32_bf16 v[108:111], v[128:131], v[168:171], v[108:111]
	v_mfma_f32_16x16x32_bf16 v[104:107], v[136:139], v[168:171], v[104:107]
	v_mfma_f32_16x16x32_bf16 v[92:95], v[128:131], v[192:195], v[92:95]
	v_mfma_f32_16x16x32_bf16 v[88:91], v[136:139], v[192:195], v[88:91]
	v_mfma_f32_16x16x32_bf16 v[76:79], v[128:131], v[206:209], v[76:79]
	v_mfma_f32_16x16x32_bf16 v[72:75], v[136:139], v[206:209], v[72:75]
	v_mfma_f32_16x16x32_bf16 v[124:127], v[132:135], v[164:167], v[124:127]
	v_mfma_f32_16x16x32_bf16 v[120:123], v[140:143], v[164:167], v[120:123]
	v_mfma_f32_16x16x32_bf16 v[108:111], v[132:135], v[172:175], v[108:111]
	v_mfma_f32_16x16x32_bf16 v[104:107], v[140:143], v[172:175], v[104:107]
	v_mfma_f32_16x16x32_bf16 v[92:95], v[132:135], v[196:199], v[92:95]
	v_mfma_f32_16x16x32_bf16 v[88:91], v[140:143], v[196:199], v[88:91]
	v_mfma_f32_16x16x32_bf16 v[76:79], v[132:135], v[210:213], v[76:79]
	v_mfma_f32_16x16x32_bf16 v[72:75], v[140:143], v[210:213], v[72:75]
	s_setprio 0
	s_setprio 1
	v_mfma_f32_16x16x32_bf16 v[116:119], v[144:147], v[160:163], v[116:119]
	v_mfma_f32_16x16x32_bf16 v[112:115], v[152:155], v[160:163], v[112:115]
	v_mfma_f32_16x16x32_bf16 v[100:103], v[144:147], v[168:171], v[100:103]
	v_mfma_f32_16x16x32_bf16 v[96:99], v[152:155], v[168:171], v[96:99]
	v_mfma_f32_16x16x32_bf16 v[84:87], v[144:147], v[192:195], v[84:87]
	v_mfma_f32_16x16x32_bf16 v[80:83], v[152:155], v[192:195], v[80:83]
	v_mfma_f32_16x16x32_bf16 v[68:71], v[144:147], v[206:209], v[68:71]
	v_mfma_f32_16x16x32_bf16 v[64:67], v[152:155], v[206:209], v[64:67]
	v_mfma_f32_16x16x32_bf16 v[116:119], v[148:151], v[164:167], v[116:119]
	v_mfma_f32_16x16x32_bf16 v[112:115], v[156:159], v[164:167], v[112:115]
	v_mfma_f32_16x16x32_bf16 v[100:103], v[148:151], v[172:175], v[100:103]
	v_mfma_f32_16x16x32_bf16 v[96:99], v[156:159], v[172:175], v[96:99]
	v_mfma_f32_16x16x32_bf16 v[84:87], v[148:151], v[196:199], v[84:87]
	v_mfma_f32_16x16x32_bf16 v[80:83], v[156:159], v[196:199], v[80:83]
	v_mfma_f32_16x16x32_bf16 v[68:71], v[148:151], v[210:213], v[68:71]
	v_mfma_f32_16x16x32_bf16 v[64:67], v[156:159], v[210:213], v[64:67]
	s_setprio 0
	s_barrier
; #define PG8_STAGE(bufoff, gbase, voff) do { _Pragma("unroll") for (int _i = 0; _i < 2; ++_i) \
;         __builtin_amdgcn_global_load_lds((const unsigned*)((const char*)(gbase) + (voff)[_i]), (PG8_LAS unsigned*)(lds + (bufoff) + ldsw + _i * 8192), 16, 0, 0); } while (0)
; #define PG8_LDA(dst, b, h) do { _Pragma("unroll") for (int m = 0; m < 4; ++m) _Pragma("unroll") for (int k = 0; k < 2; ++k) dst[m][k] = *(const PG8_LAS bf16x8*)(lds + PG8_SA(b, h) + aoff + m * 2048 + k * 1024); } while (0)
; #define PG8_MMA(ai, bj, At, Bt) do { __builtin_amdgcn_s_setprio(1); _Pragma("unroll") for (int m = 0; m < 4; ++m) _Pragma("unroll") for (int n = 0; n < 2; ++n) _Pragma("unroll") for (int k = 0; k < 2; ++k) \
;         acc[ai][bj][m][n] = __builtin_amdgcn_mfma_f32_16x16x32_bf16(Bt[n][k], At[m][k], acc[ai][bj][m][n], 0, 0, 0); __builtin_amdgcn_s_setprio(0); } while (0)
; #define PG8_WAIT_V(n) asm volatile("s_waitcnt vmcnt(" #n ")" ::: "memory")
; #define PG8_WAIT_L(n) asm volatile("s_waitcnt lgkmcnt(" #n ")" ::: "memory")
; #define PG8_BAR __builtin_amdgcn_s_barrier()
; #define PG8_SCHED __builtin_amdgcn_sched_barrier(0)
;     ...
;         for (int t = 0; t < nt; t += 2) {
;     ...
;             PG8_LDA(At, 1, 1); PG8_STAGE(PG8_SB(1, 0), b3, voffB); PG8_STAGE(PG8_SB(1, 1), b3 + hstepB, voffB); PG8_STAGE(PG8_SA(1, 0), a3, voffA);
;             PG8_WAIT_V(8); PG8_WAIT_L(0); PG8_BAR; PG8_MMA(1, 0, At, B0); PG8_MMA(1, 1, At, B1); PG8_BAR; PG8_SCHED;
	s_add_i32 s40, s48, s43
	v_lshl_add_u64 v[200:201], v[200:201], 0, s[18:19]
	s_mov_b32 m0, s40
	ds_read_b128 v[160:163], v205 offset:49152
	ds_read_b128 v[164:167], v205 offset:50176
	ds_read_b128 v[168:171], v205 offset:51200
	ds_read_b128 v[172:175], v205 offset:52224
	ds_read_b128 v[192:195], v205 offset:53248
	ds_read_b128 v[196:199], v205 offset:54272
	ds_read_b128 v[206:209], v205 offset:55296
	ds_read_b128 v[210:213], v205 offset:56320
	global_load_lds_dwordx4 v[200:201], off
	s_add_i32 m0, s40, 0x2000
	s_add_u32 s34, s34, 0x40080
	v_lshl_add_u64 v[200:201], v[214:215], 0, s[18:19]
	s_addc_u32 s35, s35, 0
	s_add_i32 s40, s49, s43
	global_load_lds_dwordx4 v[200:201], off
	v_lshl_add_u64 v[200:201], s[34:35], 0, v[178:179]
	s_mov_b32 m0, s40
	s_nop 0
	global_load_lds_dwordx4 v[200:201], off
	v_lshl_add_u64 v[200:201], s[34:35], 0, v[182:183]
	s_add_i32 m0, s40, 0x2000
	s_nop 0
	global_load_lds_dwordx4 v[200:201], off
	v_lshl_add_u64 v[200:201], v[216:217], 0, s[18:19]
	s_mov_b32 m0, s53
	s_nop 0
	global_load_lds_dwordx4 v[200:201], off
	v_lshl_add_u64 v[200:201], v[218:219], 0, s[18:19]
	s_mov_b32 m0, s54
	s_nop 0
	global_load_lds_dwordx4 v[200:201], off
	s_waitcnt vmcnt(8)
	s_waitcnt lgkmcnt(0)
	s_barrier
	s_setprio 1
	s_waitcnt lgkmcnt(0)
	v_mfma_f32_16x16x32_bf16 v[60:63], v[128:131], v[160:163], v[60:63]
	v_mfma_f32_16x16x32_bf16 v[56:59], v[136:139], v[160:163], v[56:59]
	v_mfma_f32_16x16x32_bf16 v[44:47], v[128:131], v[168:171], v[44:47]
	v_mfma_f32_16x16x32_bf16 v[40:43], v[136:139], v[168:171], v[40:43]
	v_mfma_f32_16x16x32_bf16 v[28:31], v[128:131], v[192:195], v[28:31]
	v_mfma_f32_16x16x32_bf16 v[24:27], v[136:139], v[192:195], v[24:27]
	v_mfma_f32_16x16x32_bf16 v[12:15], v[128:131], v[206:209], v[12:15]
	v_mfma_f32_16x16x32_bf16 v[8:11], v[136:139], v[206:209], v[8:11]
	v_mfma_f32_16x16x32_bf16 v[60:63], v[132:135], v[164:167], v[60:63]
	v_mfma_f32_16x16x32_bf16 v[56:59], v[140:143], v[164:167], v[56:59]
	v_mfma_f32_16x16x32_bf16 v[44:47], v[132:135], v[172:175], v[44:47]
	v_mfma_f32_16x16x32_bf16 v[40:43], v[140:143], v[172:175], v[40:43]
	v_mfma_f32_16x16x32_bf16 v[28:31], v[132:135], v[196:199], v[28:31]
	v_mfma_f32_16x16x32_bf16 v[24:27], v[140:143], v[196:199], v[24:27]
	v_mfma_f32_16x16x32_bf16 v[12:15], v[132:135], v[210:213], v[12:15]
	v_mfma_f32_16x16x32_bf16 v[8:11], v[140:143], v[210:213], v[8:11]
	s_setprio 0
	s_setprio 1
	v_mfma_f32_16x16x32_bf16 v[52:55], v[144:147], v[160:163], v[52:55]
	v_mfma_f32_16x16x32_bf16 v[48:51], v[152:155], v[160:163], v[48:51]
	v_mfma_f32_16x16x32_bf16 v[36:39], v[144:147], v[168:171], v[36:39]
	v_mfma_f32_16x16x32_bf16 v[32:35], v[152:155], v[168:171], v[32:35]
	v_mfma_f32_16x16x32_bf16 v[20:23], v[144:147], v[192:195], v[20:23]
	v_mfma_f32_16x16x32_bf16 v[16:19], v[152:155], v[192:195], v[16:19]
	v_mfma_f32_16x16x32_bf16 v[4:7], v[144:147], v[206:209], v[4:7]
	v_mfma_f32_16x16x32_bf16 v[0:3], v[152:155], v[206:209], v[0:3]
	v_mfma_f32_16x16x32_bf16 v[52:55], v[148:151], v[164:167], v[52:55]
	v_mfma_f32_16x16x32_bf16 v[48:51], v[156:159], v[164:167], v[48:51]
	v_mfma_f32_16x16x32_bf16 v[36:39], v[148:151], v[172:175], v[36:39]
	v_mfma_f32_16x16x32_bf16 v[32:35], v[156:159], v[172:175], v[32:35]
	v_mfma_f32_16x16x32_bf16 v[20:23], v[148:151], v[196:199], v[20:23]
	v_mfma_f32_16x16x32_bf16 v[16:19], v[156:159], v[196:199], v[16:19]
	v_mfma_f32_16x16x32_bf16 v[4:7], v[148:151], v[210:213], v[4:7]
	v_mfma_f32_16x16x32_bf16 v[0:3], v[156:159], v[210:213], v[0:3]
	s_setprio 0
	s_barrier
	s_add_i32 s61, s61, 2
	s_add_u32 s28, s28, 0x100
	s_addc_u32 s29, s29, 0
	s_add_u32 s59, s59, 0x100
	s_addc_u32 s60, s60, 0
	s_cmp_gt_u32 s61, 13
	s_cbranch_scc0 .LBB0_1252
	s_mov_b32 s98, 1
	s_and_b64 vcc, exec, s[20:21]
	s_cbranch_vccz .LBB0_1255
	s_barrier

; #define PG8_STAGE(bufoff, gbase, voff) do { _Pragma("unroll") for (int _i = 0; _i < 2; ++_i) \
;         __builtin_amdgcn_global_load_lds((const unsigned*)((const char*)(gbase) + (voff)[_i]), (PG8_LAS unsigned*)(lds + (bufoff) + ldsw + _i * 8192), 16, 0, 0); } while (0)
; #define PG8_WAIT_V(n) asm volatile("s_waitcnt vmcnt(" #n ")" ::: "memory")
; #define PG8_BAR __builtin_amdgcn_s_barrier()
;     ...
;     for (int i = 0; i < 2; ++i) { int R, C; stage_rc(tid * 16 + i * 8192, R, C); const int Rb = Epi::PERM ? ((R & ~31) + perm32(R & 31)) : R;
;         voffA[i] = (unsigned)(R * lda_ + C) * 2u; voffB[i] = (unsigned)(Rb * K + C) * 2u; }
;     const size_t kstep = (size_t)(BK * 2);
;     const size_t hstepA = (size_t)HALF * lda_ * 2, hstepB = (size_t)HALF * K * 2;
;     const size_t tstepA = 2 * hstepA, tstepB = 2 * hstepB;
;     const unsigned ldsw = (unsigned)wid * 1024u;
;     const int aoff = lds_byte(wr * 64 + fr, fq * 8), boff = lds_byte(wc * 32 + fr, fq * 8);
;     ...
;         PG8_STAGE(PG8_SB(1, 0), cB + kstep, voffB); PG8_STAGE(PG8_SA(1, 0), cA + kstep, voffA); PG8_STAGE(PG8_SB(1, 1), cB + hstepB + kstep, voffB);
;         PG8_WAIT_V(6); PG8_BAR;
.LBB0_1331:
	s_add_u32 s6, s0, 0x2e00000
	s_addc_u32 s7, s1, 0
	s_add_u32 s8, s0, 0xc800000
	s_addc_u32 s9, s1, 0
	s_lshl_b32 s50, s11, 6
	s_lshl_b32 s18, s11, 13
	s_lshl_b32 s0, s10, 5
	s_mov_b64 s[10:11], 0x80
	s_and_b32 s51, s0, 0x60
	s_add_i32 m0, s29, 0x18000
	v_lshl_add_u64 v[6:7], v[6:7], 0, s[10:11]
	s_lshl_b32 s19, s51, 7
	s_waitcnt vmcnt(2)
	s_barrier
	global_load_lds_dwordx4 v[6:7], off
	v_lshl_add_u64 v[4:5], v[4:5], 0, s[10:11]
	s_add_i32 m0, s29, 0x1a000
	s_add_i32 s52, s29, 0x8000
	s_add_i32 s53, s29, 0xa000
	global_load_lds_dwordx4 v[4:5], off
	v_lshl_add_u64 v[0:1], v[0:1], 0, s[10:11]
	s_mov_b32 m0, s52
	s_add_u32 s0, s36, 0x40080
	global_load_lds_dwordx4 v[0:1], off
	v_lshl_add_u64 v[0:1], v[2:3], 0, s[10:11]
	s_mov_b32 m0, s53
	s_addc_u32 s1, s37, 0
	global_load_lds_dwordx4 v[0:1], off
	s_add_i32 m0, s29, 0x1c000
	v_lshl_add_u64 v[0:1], s[0:1], 0, v[132:133]
	global_load_lds_dwordx4 v[0:1], off
	v_lshl_add_u64 v[0:1], s[0:1], 0, v[128:129]
	s_add_i32 m0, s29, 0x1e000
	s_movk_i32 s0, 0x3c0
	global_load_lds_dwordx4 v[0:1], off
	v_and_b32_e32 v0, 48, v8
	v_lshlrev_b32_e32 v1, 6, v8
	v_and_or_b32 v0, v1, s0, v0
	v_lshlrev_b32_e32 v1, 2, v8
	v_and_b32_e32 v1, 32, v1
	v_bitop3_b32 v2, v0, s18, v1 bitop3:0xde
	v_bitop3_b32 v149, s19, v0, v1 bitop3:0xf6
	v_lshlrev_b32_e32 v0, 14, v13
	v_and_b32_e32 v0, 0xffff8000, v0
	v_lshl_add_u32 v0, v12, 11, v0
	v_and_b32_e32 v1, 1, v13
	v_lshl_or_b32 v0, v1, 6, v0
	v_lshl_add_u32 v136, v14, 1, v0
	v_lshlrev_b32_e32 v0, 14, v9
	v_and_b32_e32 v0, 0xffff8000, v0
	s_waitcnt vmcnt(6)
	s_cmpk_lt_u32 s17, 0x100
	v_lshl_add_u32 v0, v10, 11, v0
	v_and_b32_e32 v1, 1, v9
	s_sext_i32_i8 s57, s16
	s_cselect_b64 s[16:17], -1, 0
	v_lshl_or_b32 v0, v1, 6, v0
	s_add_i32 s54, 0, 0x10000
	s_add_i32 s55, 0, 0x14000
	v_mov_b32_e32 v137, v133
	v_lshl_add_u32 v138, v11, 1, v0
	v_mov_b32_e32 v139, v133
	v_mov_b64_e32 v[140:141], 0x1000
	v_mov_b64_e32 v[142:143], 0xfff
	v_add_u32_e32 v151, s54, v149
	v_add_u32_e32 v153, s55, v149
	v_add_u32_e32 v157, 0, v2
	v_mov_b32_e32 v159, 0x358637bd
	s_mov_b64 s[18:19], 0x100000
	s_mov_b32 s56, 0x100000
	s_barrier
	s_mov_b32 s98, 0
	s_branch .LBB0_1334
.Lfi_p6_a:
	s_waitcnt vmcnt(32)
	s_branch .Lfi_p6_aj

; #define PG8_STAGE(bufoff, gbase, voff) do { _Pragma("unroll") for (int _i = 0; _i < 2; ++_i) \
;         __builtin_amdgcn_global_load_lds((const unsigned*)((const char*)(gbase) + (voff)[_i]), (PG8_LAS unsigned*)(lds + (bufoff) + ldsw + _i * 8192), 16, 0, 0); } while (0)
; #define PG8_LDA(dst, b, h) do { _Pragma("unroll") for (int m = 0; m < 4; ++m) _Pragma("unroll") for (int k = 0; k < 2; ++k) dst[m][k] = *(const PG8_LAS bf16x8*)(lds + PG8_SA(b, h) + aoff + m * 2048 + k * 1024); } while (0)
; #define PG8_LDB(dst, b, h) do { _Pragma("unroll") for (int n = 0; n < 2; ++n) _Pragma("unroll") for (int k = 0; k < 2; ++k) dst[n][k] = *(const PG8_LAS bf16x8*)(lds + PG8_SB(b, h) + boff + n * 2048 + k * 1024); } while (0)
; #define PG8_MMA(ai, bj, At, Bt) do { __builtin_amdgcn_s_setprio(1); _Pragma("unroll") for (int m = 0; m < 4; ++m) _Pragma("unroll") for (int n = 0; n < 2; ++n) _Pragma("unroll") for (int k = 0; k < 2; ++k) \
;         acc[ai][bj][m][n] = __builtin_amdgcn_mfma_f32_16x16x32_bf16(Bt[n][k], At[m][k], acc[ai][bj][m][n], 0, 0, 0); __builtin_amdgcn_s_setprio(0); } while (0)
; #define PG8_WAIT_V(n) asm volatile("s_waitcnt vmcnt(" #n ")" ::: "memory")
; #define PG8_WAIT_L(n) asm volatile("s_waitcnt lgkmcnt(" #n ")" ::: "memory")
; #define PG8_BAR __builtin_amdgcn_s_barrier()
; #define PG8_SCHED __builtin_amdgcn_sched_barrier(0)
;     ...
;             const char* a2 = last ? nA : cA + (size_t)(t + 2) * kstep; const char* b2 = last ? nB : cB + (size_t)(t + 2) * kstep;
;             const char* a3 = a2 + kstep; const char* b3 = b2 + kstep;
;             if (last && has_next) S.a_ready(nxt);
;             if constexpr (SP2) {
;             PG8_LDB(B0, 0, 0); PG8_LDB(B1, 0, 1); PG8_SCHED; PG8_LDA(At, 0, 0); PG8_STAGE(PG8_SA(1, 1), a1 + hstepA, voffA);
;             PG8_WAIT_V(8); PG8_WAIT_L(0); PG8_BAR; PG8_MMA(0, 0, At, B0); PG8_MMA(0, 1, At, B1); PG8_BAR; PG8_SCHED;
;             PG8_LDA(At, 0, 1); PG8_STAGE(PG8_SB(0, 0), b2, voffB); PG8_STAGE(PG8_SB(0, 1), b2 + hstepB, voffB); PG8_STAGE(PG8_SA(0, 0), a2, voffA);
.LBB0_1341:
	ds_read_b128 v[144:147], v151
	ds_read_b128 v[160:163], v151 offset:1024
	ds_read_b128 v[164:167], v151 offset:2048
	ds_read_b128 v[168:171], v151 offset:3072
	ds_read_b128 v[172:175], v153
	ds_read_b128 v[176:179], v153 offset:1024
	ds_read_b128 v[180:183], v153 offset:2048
	ds_read_b128 v[184:187], v153 offset:3072
	s_add_u32 s36, s34, 0xfffc0080
	s_addc_u32 s37, s35, -1
	s_cmp_eq_u32 s62, 12
	s_cselect_b32 s39, s23, s37
	s_cselect_b32 s38, s58, s36
	s_cselect_b32 s37, s21, s61
	s_cselect_b32 s36, s59, s60
	v_lshl_add_u64 v[154:155], s[34:35], 0, v[136:137]
	s_add_i32 m0, s29, 0xc000
	ds_read_b128 v[188:191], v157
	ds_read_b128 v[192:195], v157 offset:1024
	ds_read_b128 v[196:199], v157 offset:2048
	ds_read_b128 v[200:203], v157 offset:3072
	ds_read_b128 v[204:207], v157 offset:4096
	ds_read_b128 v[208:211], v157 offset:5120
	ds_read_b128 v[212:215], v157 offset:6144
	ds_read_b128 v[216:219], v157 offset:7168
	global_load_lds_dwordx4 v[154:155], off
	v_lshl_add_u64 v[154:155], s[34:35], 0, v[138:139]
	s_add_i32 m0, s29, 0xe000
	s_nop 0
	global_load_lds_dwordx4 v[154:155], off
	s_cmp_lg_u32 s98, 0
	s_cbranch_scc1 .Lfi_p6_a
	s_waitcnt vmcnt(8)
.Lfi_p6_aj:
	s_waitcnt lgkmcnt(0)
	s_barrier
	s_setprio 1
	s_waitcnt lgkmcnt(0)
	v_mfma_f32_16x16x32_bf16 v[124:127], v[144:147], v[188:191], v[124:127]
	v_mfma_f32_16x16x32_bf16 v[120:123], v[164:167], v[188:191], v[120:123]
	v_mfma_f32_16x16x32_bf16 v[108:111], v[144:147], v[196:199], v[108:111]
	v_mfma_f32_16x16x32_bf16 v[104:107], v[164:167], v[196:199], v[104:107]
	v_mfma_f32_16x16x32_bf16 v[92:95], v[144:147], v[204:207], v[92:95]
	v_mfma_f32_16x16x32_bf16 v[88:91], v[164:167], v[204:207], v[88:91]
	v_mfma_f32_16x16x32_bf16 v[76:79], v[144:147], v[212:215], v[76:79]
	v_mfma_f32_16x16x32_bf16 v[72:75], v[164:167], v[212:215], v[72:75]
	v_mfma_f32_16x16x32_bf16 v[124:127], v[160:163], v[192:195], v[124:127]
	v_mfma_f32_16x16x32_bf16 v[120:123], v[168:171], v[192:195], v[120:123]
	v_mfma_f32_16x16x32_bf16 v[108:111], v[160:163], v[200:203], v[108:111]
	v_mfma_f32_16x16x32_bf16 v[104:107], v[168:171], v[200:203], v[104:107]
	v_mfma_f32_16x16x32_bf16 v[92:95], v[160:163], v[208:211], v[92:95]
	v_mfma_f32_16x16x32_bf16 v[88:91], v[168:171], v[208:211], v[88:91]
	v_mfma_f32_16x16x32_bf16 v[76:79], v[160:163], v[216:219], v[76:79]
	v_mfma_f32_16x16x32_bf16 v[72:75], v[168:171], v[216:219], v[72:75]
	s_setprio 0
	s_setprio 1
	v_mfma_f32_16x16x32_bf16 v[116:119], v[172:175], v[188:191], v[116:119]
	v_mfma_f32_16x16x32_bf16 v[112:115], v[180:183], v[188:191], v[112:115]
	v_mfma_f32_16x16x32_bf16 v[100:103], v[172:175], v[196:199], v[100:103]
	v_mfma_f32_16x16x32_bf16 v[96:99], v[180:183], v[196:199], v[96:99]
	v_mfma_f32_16x16x32_bf16 v[84:87], v[172:175], v[204:207], v[84:87]
	v_mfma_f32_16x16x32_bf16 v[80:83], v[180:183], v[204:207], v[80:83]
	v_mfma_f32_16x16x32_bf16 v[68:71], v[172:175], v[212:215], v[68:71]
	v_mfma_f32_16x16x32_bf16 v[64:67], v[180:183], v[212:215], v[64:67]
	v_mfma_f32_16x16x32_bf16 v[116:119], v[176:179], v[192:195], v[116:119]
	v_mfma_f32_16x16x32_bf16 v[112:115], v[184:187], v[192:195], v[112:115]
	v_mfma_f32_16x16x32_bf16 v[100:103], v[176:179], v[200:203], v[100:103]
	v_mfma_f32_16x16x32_bf16 v[96:99], v[184:187], v[200:203], v[96:99]
	v_mfma_f32_16x16x32_bf16 v[84:87], v[176:179], v[208:211], v[84:87]
	v_mfma_f32_16x16x32_bf16 v[80:83], v[184:187], v[208:211], v[80:83]
	v_mfma_f32_16x16x32_bf16 v[68:71], v[176:179], v[216:219], v[68:71]
	v_mfma_f32_16x16x32_bf16 v[64:67], v[184:187], v[216:219], v[64:67]
	s_setprio 0
	s_barrier
	s_add_i32 s48, s54, s43
	v_lshl_add_u64 v[154:155], s[36:37], 0, v[132:133]
	s_mov_b32 m0, s48
	ds_read_b128 v[188:191], v157 offset:16384
	ds_read_b128 v[192:195], v157 offset:17408
	ds_read_b128 v[196:199], v157 offset:18432
	ds_read_b128 v[200:203], v157 offset:19456
	ds_read_b128 v[204:207], v157 offset:20480
	ds_read_b128 v[208:211], v157 offset:21504
	ds_read_b128 v[212:215], v157 offset:22528
	ds_read_b128 v[216:219], v157 offset:23552
	global_load_lds_dwordx4 v[154:155], off
	s_add_i32 m0, s48, 0x2000
	s_add_u32 s48, s36, 0x40000
	v_lshl_add_u64 v[220:221], s[36:37], 0, v[128:129]
	s_addc_u32 s49, s37, 0
	s_add_i32 s63, s55, s43
	global_load_lds_dwordx4 v[220:221], off
	v_lshl_add_u64 v[222:223], s[48:49], 0, v[132:133]
	s_mov_b32 m0, s63
	v_lshl_add_u64 v[224:225], s[38:39], 0, v[130:131]
	global_load_lds_dwordx4 v[222:223], off
	v_lshl_add_u64 v[222:223], s[48:49], 0, v[128:129]
	s_add_i32 m0, s63, 0x2000
	s_nop 0
	global_load_lds_dwordx4 v[222:223], off
	v_lshl_add_u64 v[222:223], s[38:39], 0, v[134:135]
	s_mov_b32 m0, s29
	s_nop 0
	global_load_lds_dwordx4 v[222:223], off
	s_mov_b32 m0, s44
	s_nop 0
	global_load_lds_dwordx4 v[224:225], off
	s_cmp_lg_u32 s98, 0
	s_cbranch_scc1 .Lfi_p6_b
	s_waitcnt vmcnt(8)
; #define PG8_STAGE(bufoff, gbase, voff) do { _Pragma("unroll") for (int _i = 0; _i < 2; ++_i) \
;         __builtin_amdgcn_global_load_lds((const unsigned*)((const char*)(gbase) + (voff)[_i]), (PG8_LAS unsigned*)(lds + (bufoff) + ldsw + _i * 8192), 16, 0, 0); } while (0)
; #define PG8_LDA(dst, b, h) do { _Pragma("unroll") for (int m = 0; m < 4; ++m) _Pragma("unroll") for (int k = 0; k < 2; ++k) dst[m][k] = *(const PG8_LAS bf16x8*)(lds + PG8_SA(b, h) + aoff + m * 2048 + k * 1024); } while (0)
; #define PG8_LDB(dst, b, h) do { _Pragma("unroll") for (int n = 0; n < 2; ++n) _Pragma("unroll") for (int k = 0; k < 2; ++k) dst[n][k] = *(const PG8_LAS bf16x8*)(lds + PG8_SB(b, h) + boff + n * 2048 + k * 1024); } while (0)
; #define PG8_MMA(ai, bj, At, Bt) do { __builtin_amdgcn_s_setprio(1); _Pragma("unroll") for (int m = 0; m < 4; ++m) _Pragma("unroll") for (int n = 0; n < 2; ++n) _Pragma("unroll") for (int k = 0; k < 2; ++k) \
;         acc[ai][bj][m][n] = __builtin_amdgcn_mfma_f32_16x16x32_bf16(Bt[n][k], At[m][k], acc[ai][bj][m][n], 0, 0, 0); __builtin_amdgcn_s_setprio(0); } while (0)
; #define PG8_WAIT_V(n) asm volatile("s_waitcnt vmcnt(" #n ")" ::: "memory")
; #define PG8_WAIT_L(n) asm volatile("s_waitcnt lgkmcnt(" #n ")" ::: "memory")
; #define PG8_BAR __builtin_amdgcn_s_barrier()
; #define PG8_SCHED __builtin_amdgcn_sched_barrier(0)
;     ...
;             PG8_WAIT_V(8); PG8_WAIT_L(0); PG8_BAR; PG8_MMA(1, 0, At, B0); PG8_MMA(1, 1, At, B1); PG8_BAR; PG8_SCHED;
;             PG8_LDB(B0, 1, 0); PG8_LDB(B1, 1, 1); PG8_SCHED; PG8_LDA(At, 1, 0); PG8_STAGE(PG8_SA(0, 1), a2 + hstepA, voffA);
;             PG8_WAIT_V(8); PG8_WAIT_L(0); PG8_BAR; PG8_MMA(0, 0, At, B0); PG8_MMA(0, 1, At, B1); PG8_BAR; PG8_SCHED;
.Lfi_p6_bj:
	s_mov_b32 s98, 0
	s_waitcnt lgkmcnt(0)
	s_barrier
	s_setprio 1
	s_waitcnt lgkmcnt(0)
	v_mfma_f32_16x16x32_bf16 v[60:63], v[144:147], v[188:191], v[60:63]
	v_mfma_f32_16x16x32_bf16 v[56:59], v[164:167], v[188:191], v[56:59]
	v_mfma_f32_16x16x32_bf16 v[44:47], v[144:147], v[196:199], v[44:47]
	v_mfma_f32_16x16x32_bf16 v[40:43], v[164:167], v[196:199], v[40:43]
	v_mfma_f32_16x16x32_bf16 v[28:31], v[144:147], v[204:207], v[28:31]
	v_mfma_f32_16x16x32_bf16 v[24:27], v[164:167], v[204:207], v[24:27]
	v_mfma_f32_16x16x32_bf16 v[12:15], v[144:147], v[212:215], v[12:15]
	v_mfma_f32_16x16x32_bf16 v[8:11], v[164:167], v[212:215], v[8:11]
	v_mfma_f32_16x16x32_bf16 v[60:63], v[160:163], v[192:195], v[60:63]
	v_mfma_f32_16x16x32_bf16 v[56:59], v[168:171], v[192:195], v[56:59]
	v_mfma_f32_16x16x32_bf16 v[44:47], v[160:163], v[200:203], v[44:47]
	v_mfma_f32_16x16x32_bf16 v[40:43], v[168:171], v[200:203], v[40:43]
	v_mfma_f32_16x16x32_bf16 v[28:31], v[160:163], v[208:211], v[28:31]
	v_mfma_f32_16x16x32_bf16 v[24:27], v[168:171], v[208:211], v[24:27]
	v_mfma_f32_16x16x32_bf16 v[12:15], v[160:163], v[216:219], v[12:15]
	v_mfma_f32_16x16x32_bf16 v[8:11], v[168:171], v[216:219], v[8:11]
	s_setprio 0
	s_setprio 1
	v_mfma_f32_16x16x32_bf16 v[52:55], v[172:175], v[188:191], v[52:55]
	v_mfma_f32_16x16x32_bf16 v[48:51], v[180:183], v[188:191], v[48:51]
	v_mfma_f32_16x16x32_bf16 v[36:39], v[172:175], v[196:199], v[36:39]
	v_mfma_f32_16x16x32_bf16 v[32:35], v[180:183], v[196:199], v[32:35]
	v_mfma_f32_16x16x32_bf16 v[20:23], v[172:175], v[204:207], v[20:23]
	v_mfma_f32_16x16x32_bf16 v[16:19], v[180:183], v[204:207], v[16:19]
	v_mfma_f32_16x16x32_bf16 v[4:7], v[172:175], v[212:215], v[4:7]
	v_mfma_f32_16x16x32_bf16 v[0:3], v[180:183], v[212:215], v[0:3]
	v_mfma_f32_16x16x32_bf16 v[52:55], v[176:179], v[192:195], v[52:55]
	v_mfma_f32_16x16x32_bf16 v[48:51], v[184:187], v[192:195], v[48:51]
	v_mfma_f32_16x16x32_bf16 v[36:39], v[176:179], v[200:203], v[36:39]
	v_mfma_f32_16x16x32_bf16 v[32:35], v[184:187], v[200:203], v[32:35]
	v_mfma_f32_16x16x32_bf16 v[20:23], v[176:179], v[208:211], v[20:23]
	v_mfma_f32_16x16x32_bf16 v[16:19], v[184:187], v[208:211], v[16:19]
	v_mfma_f32_16x16x32_bf16 v[4:7], v[176:179], v[216:219], v[4:7]
	v_mfma_f32_16x16x32_bf16 v[0:3], v[184:187], v[216:219], v[0:3]
	s_setprio 0
	s_barrier
	s_add_i32 s48, 0, 0x18000
	v_add_u32_e32 v148, s48, v149
	s_add_i32 s49, 0, 0x1c000
	ds_read_b128 v[144:147], v148
	ds_read_b128 v[160:163], v148 offset:1024
	ds_read_b128 v[164:167], v148 offset:2048
	ds_read_b128 v[168:171], v148 offset:3072
	v_add_u32_e32 v148, s49, v149
	ds_read_b128 v[172:175], v148
	ds_read_b128 v[176:179], v148 offset:1024
	ds_read_b128 v[180:183], v148 offset:2048
	ds_read_b128 v[184:187], v148 offset:3072
	s_add_u32 s38, s38, 0x40000
	s_addc_u32 s39, s39, 0
	s_mov_b32 m0, s45
	v_lshl_add_u64 v[226:227], s[38:39], 0, v[134:135]
	ds_read_b128 v[188:191], v157 offset:32768
	ds_read_b128 v[192:195], v157 offset:33792
	ds_read_b128 v[196:199], v157 offset:34816
	ds_read_b128 v[200:203], v157 offset:35840
	ds_read_b128 v[204:207], v157 offset:36864
	ds_read_b128 v[208:211], v157 offset:37888
	ds_read_b128 v[212:215], v157 offset:38912
	ds_read_b128 v[216:219], v157 offset:39936
	global_load_lds_dwordx4 v[226:227], off
	v_lshl_add_u64 v[226:227], s[38:39], 0, v[130:131]
	s_mov_b32 m0, s46
	s_nop 0
	global_load_lds_dwordx4 v[226:227], off
	s_waitcnt vmcnt(8)
	s_waitcnt lgkmcnt(0)
	s_barrier
	s_setprio 1
	s_waitcnt lgkmcnt(0)
	v_mfma_f32_16x16x32_bf16 v[124:127], v[144:147], v[188:191], v[124:127]
	v_mfma_f32_16x16x32_bf16 v[120:123], v[164:167], v[188:191], v[120:123]
	v_mfma_f32_16x16x32_bf16 v[108:111], v[144:147], v[196:199], v[108:111]
	v_mfma_f32_16x16x32_bf16 v[104:107], v[164:167], v[196:199], v[104:107]
	v_mfma_f32_16x16x32_bf16 v[92:95], v[144:147], v[204:207], v[92:95]
	v_mfma_f32_16x16x32_bf16 v[88:91], v[164:167], v[204:207], v[88:91]
	v_mfma_f32_16x16x32_bf16 v[76:79], v[144:147], v[212:215], v[76:79]
	v_mfma_f32_16x16x32_bf16 v[72:75], v[164:167], v[212:215], v[72:75]
	v_mfma_f32_16x16x32_bf16 v[124:127], v[160:163], v[192:195], v[124:127]
	v_mfma_f32_16x16x32_bf16 v[120:123], v[168:171], v[192:195], v[120:123]
	v_mfma_f32_16x16x32_bf16 v[108:111], v[160:163], v[200:203], v[108:111]
	v_mfma_f32_16x16x32_bf16 v[104:107], v[168:171], v[200:203], v[104:107]
	v_mfma_f32_16x16x32_bf16 v[92:95], v[160:163], v[208:211], v[92:95]
	v_mfma_f32_16x16x32_bf16 v[88:91], v[168:171], v[208:211], v[88:91]
	v_mfma_f32_16x16x32_bf16 v[76:79], v[160:163], v[216:219], v[76:79]
	v_mfma_f32_16x16x32_bf16 v[72:75], v[168:171], v[216:219], v[72:75]
	s_setprio 0
	s_setprio 1
	v_mfma_f32_16x16x32_bf16 v[116:119], v[172:175], v[188:191], v[116:119]
	v_mfma_f32_16x16x32_bf16 v[112:115], v[180:183], v[188:191], v[112:115]
	v_mfma_f32_16x16x32_bf16 v[100:103], v[172:175], v[196:199], v[100:103]
	v_mfma_f32_16x16x32_bf16 v[96:99], v[180:183], v[196:199], v[96:99]
	v_mfma_f32_16x16x32_bf16 v[84:87], v[172:175], v[204:207], v[84:87]
	v_mfma_f32_16x16x32_bf16 v[80:83], v[180:183], v[204:207], v[80:83]
	v_mfma_f32_16x16x32_bf16 v[68:71], v[172:175], v[212:215], v[68:71]
	v_mfma_f32_16x16x32_bf16 v[64:67], v[180:183], v[212:215], v[64:67]
	v_mfma_f32_16x16x32_bf16 v[116:119], v[176:179], v[192:195], v[116:119]
	v_mfma_f32_16x16x32_bf16 v[112:115], v[184:187], v[192:195], v[112:115]
	v_mfma_f32_16x16x32_bf16 v[100:103], v[176:179], v[200:203], v[100:103]
	v_mfma_f32_16x16x32_bf16 v[96:99], v[184:187], v[200:203], v[96:99]
	v_mfma_f32_16x16x32_bf16 v[84:87], v[176:179], v[208:211], v[84:87]
	v_mfma_f32_16x16x32_bf16 v[80:83], v[184:187], v[208:211], v[80:83]
	v_mfma_f32_16x16x32_bf16 v[68:71], v[176:179], v[216:219], v[68:71]
	v_mfma_f32_16x16x32_bf16 v[64:67], v[184:187], v[216:219], v[64:67]
	s_setprio 0
	s_barrier
; #define PG8_STAGE(bufoff, gbase, voff) do { _Pragma("unroll") for (int _i = 0; _i < 2; ++_i) \
;         __builtin_amdgcn_global_load_lds((const unsigned*)((const char*)(gbase) + (voff)[_i]), (PG8_LAS unsigned*)(lds + (bufoff) + ldsw + _i * 8192), 16, 0, 0); } while (0)
; #define PG8_LDA(dst, b, h) do { _Pragma("unroll") for (int m = 0; m < 4; ++m) _Pragma("unroll") for (int k = 0; k < 2; ++k) dst[m][k] = *(const PG8_LAS bf16x8*)(lds + PG8_SA(b, h) + aoff + m * 2048 + k * 1024); } while (0)
; #define PG8_MMA(ai, bj, At, Bt) do { __builtin_amdgcn_s_setprio(1); _Pragma("unroll") for (int m = 0; m < 4; ++m) _Pragma("unroll") for (int n = 0; n < 2; ++n) _Pragma("unroll") for (int k = 0; k < 2; ++k) \
;         acc[ai][bj][m][n] = __builtin_amdgcn_mfma_f32_16x16x32_bf16(Bt[n][k], At[m][k], acc[ai][bj][m][n], 0, 0, 0); __builtin_amdgcn_s_setprio(0); } while (0)
; #define PG8_WAIT_V(n) asm volatile("s_waitcnt vmcnt(" #n ")" ::: "memory")
; #define PG8_WAIT_L(n) asm volatile("s_waitcnt lgkmcnt(" #n ")" ::: "memory")
; #define PG8_BAR __builtin_amdgcn_s_barrier()
; #define PG8_SCHED __builtin_amdgcn_sched_barrier(0)
;     ...
;         for (int t = 0; t < nt; t += 2) {
;     ...
;             PG8_LDA(At, 1, 1); PG8_STAGE(PG8_SB(1, 0), b3, voffB); PG8_STAGE(PG8_SB(1, 1), b3 + hstepB, voffB); PG8_STAGE(PG8_SA(1, 0), a3, voffA);
;             PG8_WAIT_V(8); PG8_WAIT_L(0); PG8_BAR; PG8_MMA(1, 0, At, B0); PG8_MMA(1, 1, At, B1); PG8_BAR; PG8_SCHED;
	s_add_i32 s38, s48, s43
	v_lshl_add_u64 v[154:155], v[154:155], 0, s[10:11]
	s_mov_b32 m0, s38
	ds_read_b128 v[188:191], v157 offset:49152
	ds_read_b128 v[192:195], v157 offset:50176
	ds_read_b128 v[196:199], v157 offset:51200
	ds_read_b128 v[200:203], v157 offset:52224
	ds_read_b128 v[204:207], v157 offset:53248
	ds_read_b128 v[208:211], v157 offset:54272
	ds_read_b128 v[212:215], v157 offset:55296
	ds_read_b128 v[216:219], v157 offset:56320
	global_load_lds_dwordx4 v[154:155], off
	s_add_i32 m0, s38, 0x2000
	s_add_u32 s36, s36, 0x40080
	v_lshl_add_u64 v[154:155], v[220:221], 0, s[10:11]
	s_addc_u32 s37, s37, 0
	s_add_i32 s38, s49, s43
	global_load_lds_dwordx4 v[154:155], off
	v_lshl_add_u64 v[154:155], s[36:37], 0, v[132:133]
	s_mov_b32 m0, s38
	s_nop 0
	global_load_lds_dwordx4 v[154:155], off
	v_lshl_add_u64 v[154:155], s[36:37], 0, v[128:129]
	s_add_i32 m0, s38, 0x2000
	s_nop 0
	global_load_lds_dwordx4 v[154:155], off
	v_lshl_add_u64 v[154:155], v[222:223], 0, s[10:11]
	s_mov_b32 m0, s52
	s_nop 0
	global_load_lds_dwordx4 v[154:155], off
	v_lshl_add_u64 v[154:155], v[224:225], 0, s[10:11]
	s_mov_b32 m0, s53
	s_nop 0
	global_load_lds_dwordx4 v[154:155], off
	s_waitcnt vmcnt(8)
	s_waitcnt lgkmcnt(0)
	s_barrier
	s_setprio 1
	s_waitcnt lgkmcnt(0)
	v_mfma_f32_16x16x32_bf16 v[60:63], v[144:147], v[188:191], v[60:63]
	v_mfma_f32_16x16x32_bf16 v[56:59], v[164:167], v[188:191], v[56:59]
	v_mfma_f32_16x16x32_bf16 v[44:47], v[144:147], v[196:199], v[44:47]
	v_mfma_f32_16x16x32_bf16 v[40:43], v[164:167], v[196:199], v[40:43]
	v_mfma_f32_16x16x32_bf16 v[28:31], v[144:147], v[204:207], v[28:31]
	v_mfma_f32_16x16x32_bf16 v[24:27], v[164:167], v[204:207], v[24:27]
	v_mfma_f32_16x16x32_bf16 v[12:15], v[144:147], v[212:215], v[12:15]
	v_mfma_f32_16x16x32_bf16 v[8:11], v[164:167], v[212:215], v[8:11]
	v_mfma_f32_16x16x32_bf16 v[60:63], v[160:163], v[192:195], v[60:63]
	v_mfma_f32_16x16x32_bf16 v[56:59], v[168:171], v[192:195], v[56:59]
	v_mfma_f32_16x16x32_bf16 v[44:47], v[160:163], v[200:203], v[44:47]
	v_mfma_f32_16x16x32_bf16 v[40:43], v[168:171], v[200:203], v[40:43]
	v_mfma_f32_16x16x32_bf16 v[28:31], v[160:163], v[208:211], v[28:31]
	v_mfma_f32_16x16x32_bf16 v[24:27], v[168:171], v[208:211], v[24:27]
	v_mfma_f32_16x16x32_bf16 v[12:15], v[160:163], v[216:219], v[12:15]
	v_mfma_f32_16x16x32_bf16 v[8:11], v[168:171], v[216:219], v[8:11]
	s_setprio 0
	s_setprio 1
	v_mfma_f32_16x16x32_bf16 v[52:55], v[172:175], v[188:191], v[52:55]
	v_mfma_f32_16x16x32_bf16 v[48:51], v[180:183], v[188:191], v[48:51]
	v_mfma_f32_16x16x32_bf16 v[36:39], v[172:175], v[196:199], v[36:39]
	v_mfma_f32_16x16x32_bf16 v[32:35], v[180:183], v[196:199], v[32:35]
	v_mfma_f32_16x16x32_bf16 v[20:23], v[172:175], v[204:207], v[20:23]
	v_mfma_f32_16x16x32_bf16 v[16:19], v[180:183], v[204:207], v[16:19]
	v_mfma_f32_16x16x32_bf16 v[4:7], v[172:175], v[212:215], v[4:7]
	v_mfma_f32_16x16x32_bf16 v[0:3], v[180:183], v[212:215], v[0:3]
	v_mfma_f32_16x16x32_bf16 v[52:55], v[176:179], v[192:195], v[52:55]
	v_mfma_f32_16x16x32_bf16 v[48:51], v[184:187], v[192:195], v[48:51]
	v_mfma_f32_16x16x32_bf16 v[36:39], v[176:179], v[200:203], v[36:39]
	v_mfma_f32_16x16x32_bf16 v[32:35], v[184:187], v[200:203], v[32:35]
	v_mfma_f32_16x16x32_bf16 v[20:23], v[176:179], v[208:211], v[20:23]
	v_mfma_f32_16x16x32_bf16 v[16:19], v[184:187], v[208:211], v[16:19]
	v_mfma_f32_16x16x32_bf16 v[4:7], v[176:179], v[216:219], v[4:7]
	v_mfma_f32_16x16x32_bf16 v[0:3], v[184:187], v[216:219], v[0:3]
	s_setprio 0
	s_barrier
	s_add_i32 s62, s62, 2
	s_add_u32 s34, s34, 0x100
	s_addc_u32 s35, s35, 0
	s_add_u32 s60, s60, 0x100
	s_addc_u32 s61, s61, 0
	s_cmp_gt_u32 s62, 13
	s_cbranch_scc0 .LBB0_1341
	s_mov_b32 s98, 1
	s_and_b64 vcc, exec, s[16:17]
	s_cbranch_vccz .LBB0_1344
	s_barrier

; #define PG8_STAGE(bufoff, gbase, voff) do { _Pragma("unroll") for (int _i = 0; _i < 2; ++_i) \
;         __builtin_amdgcn_global_load_lds((const unsigned*)((const char*)(gbase) + (voff)[_i]), (PG8_LAS unsigned*)(lds + (bufoff) + ldsw + _i * 8192), 16, 0, 0); } while (0)
; #define PG8_WAIT_V(n) asm volatile("s_waitcnt vmcnt(" #n ")" ::: "memory")
; #define PG8_BAR __builtin_amdgcn_s_barrier()
;     ...
;     for (int i = 0; i < 2; ++i) { int R, C; stage_rc(tid * 16 + i * 8192, R, C); const int Rb = Epi::PERM ? ((R & ~31) + perm32(R & 31)) : R;
;         voffA[i] = (unsigned)(R * lda_ + C) * 2u; voffB[i] = (unsigned)(Rb * K + C) * 2u; }
;     const size_t kstep = (size_t)(BK * 2);
;     const size_t hstepA = (size_t)HALF * lda_ * 2, hstepB = (size_t)HALF * K * 2;
;     const size_t tstepA = 2 * hstepA, tstepB = 2 * hstepB;
;     const unsigned ldsw = (unsigned)wid * 1024u;
;     const int aoff = lds_byte(wr * 64 + fr, fq * 8), boff = lds_byte(wc * 32 + fr, fq * 8);
;     ...
;         PG8_STAGE(PG8_SB(1, 0), cB + kstep, voffB); PG8_STAGE(PG8_SA(1, 0), cA + kstep, voffA); PG8_STAGE(PG8_SB(1, 1), cB + hstepB + kstep, voffB);
;         PG8_WAIT_V(6); PG8_BAR;
.LBB0_1404:
	s_add_u32 s6, s6, 0x4800000
	s_addc_u32 s7, s7, 0
	s_lshl_b32 s42, s15, 6
	s_lshl_b32 s18, s15, 13
	s_lshl_b32 s1, s1, 5
	s_mov_b64 s[14:15], 0x80
	s_and_b32 s43, s1, 0x60
	s_add_i32 m0, s8, 0x18000
	v_lshl_add_u64 v[6:7], v[6:7], 0, s[14:15]
	s_lshl_b32 s1, s43, 7
	s_waitcnt vmcnt(2)
	s_barrier
	global_load_lds_dwordx4 v[6:7], off
	v_lshl_add_u64 v[4:5], v[4:5], 0, s[14:15]
	s_add_i32 m0, s8, 0x1a000
	s_add_i32 s44, s8, 0x8000
	s_add_i32 s45, s8, 0xa000
	global_load_lds_dwordx4 v[4:5], off
	v_lshl_add_u64 v[0:1], v[0:1], 0, s[14:15]
	s_mov_b32 m0, s44
	s_add_u32 s16, s28, 0x100080
	global_load_lds_dwordx4 v[0:1], off
	v_lshl_add_u64 v[0:1], v[2:3], 0, s[14:15]
	s_mov_b32 m0, s45
	s_addc_u32 s17, s29, 0
	global_load_lds_dwordx4 v[0:1], off
	s_add_i32 m0, s8, 0x1c000
	v_lshl_add_u64 v[0:1], s[16:17], 0, v[140:141]
	global_load_lds_dwordx4 v[0:1], off
	v_lshl_add_u64 v[0:1], s[16:17], 0, v[136:137]
	s_add_i32 m0, s8, 0x1e000
	s_movk_i32 s16, 0x3c0
	global_load_lds_dwordx4 v[0:1], off
	v_and_b32_e32 v0, 48, v232
	v_lshlrev_b32_e32 v1, 6, v232
	v_and_or_b32 v0, v1, s16, v0
	v_lshlrev_b32_e32 v1, 2, v232
	v_and_b32_e32 v1, 32, v1
	v_bitop3_b32 v2, v0, s18, v1 bitop3:0xde
	v_bitop3_b32 v162, s1, v0, v1 bitop3:0xf6
	v_lshlrev_b32_e32 v0, 16, v12
	v_and_b32_e32 v0, 0xfffe0000, v0
	v_lshl_add_u32 v0, v11, 13, v0
	v_and_b32_e32 v1, 1, v12
	v_lshl_or_b32 v0, v1, 6, v0
	v_lshl_add_u32 v144, v13, 1, v0
	v_lshlrev_b32_e32 v0, 16, v8
	v_and_b32_e32 v0, 0xfffe0000, v0
	s_waitcnt vmcnt(6)
	s_cmpk_lt_u32 s0, 0x100
	v_lshl_add_u32 v0, v9, 13, v0
	v_and_b32_e32 v1, 1, v8
	s_cselect_b64 s[16:17], -1, 0
	v_lshl_or_b32 v0, v1, 6, v0
	s_add_i32 s46, 0, 0x10000
	s_add_i32 s47, 0, 0x14000
	v_mov_b32_e32 v145, v141
	v_lshl_add_u32 v146, v10, 1, v0
	v_mov_b32_e32 v147, v141
	v_mov_b64_e32 v[148:149], 0x400
	v_mov_b64_e32 v[150:151], 0x3ff
	v_add_u32_e32 v163, s46, v162
	v_add_u32_e32 v164, s47, v162
	v_add_u32_e32 v165, 0, v2
	s_barrier
	s_mov_b32 s98, 0
	s_branch .LBB0_1407

; #define PG8_STAGE(bufoff, gbase, voff) do { _Pragma("unroll") for (int _i = 0; _i < 2; ++_i) \
;         __builtin_amdgcn_global_load_lds((const unsigned*)((const char*)(gbase) + (voff)[_i]), (PG8_LAS unsigned*)(lds + (bufoff) + ldsw + _i * 8192), 16, 0, 0); } while (0)
; #define PG8_LDA(dst, b, h) do { _Pragma("unroll") for (int m = 0; m < 4; ++m) _Pragma("unroll") for (int k = 0; k < 2; ++k) dst[m][k] = *(const PG8_LAS bf16x8*)(lds + PG8_SA(b, h) + aoff + m * 2048 + k * 1024); } while (0)
; #define PG8_LDB(dst, b, h) do { _Pragma("unroll") for (int n = 0; n < 2; ++n) _Pragma("unroll") for (int k = 0; k < 2; ++k) dst[n][k] = *(const PG8_LAS bf16x8*)(lds + PG8_SB(b, h) + boff + n * 2048 + k * 1024); } while (0)
; #define PG8_MMA(ai, bj, At, Bt) do { __builtin_amdgcn_s_setprio(1); _Pragma("unroll") for (int m = 0; m < 4; ++m) _Pragma("unroll") for (int n = 0; n < 2; ++n) _Pragma("unroll") for (int k = 0; k < 2; ++k) \
;         acc[ai][bj][m][n] = __builtin_amdgcn_mfma_f32_16x16x32_bf16(Bt[n][k], At[m][k], acc[ai][bj][m][n], 0, 0, 0); __builtin_amdgcn_s_setprio(0); } while (0)
; #define PG8_WAIT_V(n) asm volatile("s_waitcnt vmcnt(" #n ")" ::: "memory")
; #define PG8_WAIT_L(n) asm volatile("s_waitcnt lgkmcnt(" #n ")" ::: "memory")
; #define PG8_BAR __builtin_amdgcn_s_barrier()
; #define PG8_SCHED __builtin_amdgcn_sched_barrier(0)
;     ...
;             const char* a2 = last ? nA : cA + (size_t)(t + 2) * kstep; const char* b2 = last ? nB : cB + (size_t)(t + 2) * kstep;
;             const char* a3 = a2 + kstep; const char* b3 = b2 + kstep;
;             if (last && has_next) S.a_ready(nxt);
;             if constexpr (SP2) {
;             PG8_LDB(B0, 0, 0); PG8_LDB(B1, 0, 1); PG8_SCHED; PG8_LDA(At, 0, 0); PG8_STAGE(PG8_SA(1, 1), a1 + hstepA, voffA);
;             PG8_WAIT_V(8); PG8_WAIT_L(0); PG8_BAR; PG8_MMA(0, 0, At, B0); PG8_MMA(0, 1, At, B1); PG8_BAR; PG8_SCHED;
;             PG8_LDA(At, 0, 1); PG8_STAGE(PG8_SB(0, 0), b2, voffB); PG8_STAGE(PG8_SB(0, 1), b2 + hstepB, voffB); PG8_STAGE(PG8_SA(0, 0), a2, voffA);
.LBB0_1414:
	ds_read_b128 v[128:131], v163
	ds_read_b128 v[132:135], v163 offset:1024
	ds_read_b128 v[152:155], v163 offset:2048
	ds_read_b128 v[156:159], v163 offset:3072
	ds_read_b128 v[166:169], v164
	ds_read_b128 v[170:173], v164 offset:1024
	ds_read_b128 v[174:177], v164 offset:2048
	ds_read_b128 v[178:181], v164 offset:3072
	s_add_u32 s28, s26, 0xfff00080
	s_addc_u32 s29, s27, -1
	s_cmp_eq_u32 s52, 60
	s_cselect_b32 s35, s21, s29
	s_cselect_b32 s34, s48, s28
	s_cselect_b32 s29, s19, s51
	s_cselect_b32 s28, s49, s50
	v_lshl_add_u64 v[160:161], s[26:27], 0, v[144:145]
	s_add_i32 m0, s8, 0xc000
	ds_read_b128 v[182:185], v165
	ds_read_b128 v[186:189], v165 offset:1024
	ds_read_b128 v[190:193], v165 offset:2048
	ds_read_b128 v[194:197], v165 offset:3072
	ds_read_b128 v[198:201], v165 offset:4096
	ds_read_b128 v[202:205], v165 offset:5120
	ds_read_b128 v[206:209], v165 offset:6144
	ds_read_b128 v[210:213], v165 offset:7168
	global_load_lds_dwordx4 v[160:161], off
	v_lshl_add_u64 v[160:161], s[26:27], 0, v[146:147]
	s_add_i32 m0, s8, 0xe000
	s_nop 0
	global_load_lds_dwordx4 v[160:161], off
	s_cmp_lg_u32 s98, 0
	s_cbranch_scc1 .Lfi_p7_a
	s_waitcnt vmcnt(8)
.Lfi_p7_aj:
	s_waitcnt lgkmcnt(0)
	s_barrier
	s_setprio 1
	s_waitcnt lgkmcnt(0)
	v_mfma_f32_16x16x32_bf16 v[124:127], v[128:131], v[182:185], v[124:127]
	v_mfma_f32_16x16x32_bf16 v[120:123], v[152:155], v[182:185], v[120:123]
	v_mfma_f32_16x16x32_bf16 v[108:111], v[128:131], v[190:193], v[108:111]
	v_mfma_f32_16x16x32_bf16 v[104:107], v[152:155], v[190:193], v[104:107]
	v_mfma_f32_16x16x32_bf16 v[92:95], v[128:131], v[198:201], v[92:95]
	v_mfma_f32_16x16x32_bf16 v[88:91], v[152:155], v[198:201], v[88:91]
	v_mfma_f32_16x16x32_bf16 v[76:79], v[128:131], v[206:209], v[76:79]
	v_mfma_f32_16x16x32_bf16 v[72:75], v[152:155], v[206:209], v[72:75]
	v_mfma_f32_16x16x32_bf16 v[124:127], v[132:135], v[186:189], v[124:127]
	v_mfma_f32_16x16x32_bf16 v[120:123], v[156:159], v[186:189], v[120:123]
	v_mfma_f32_16x16x32_bf16 v[108:111], v[132:135], v[194:197], v[108:111]
	v_mfma_f32_16x16x32_bf16 v[104:107], v[156:159], v[194:197], v[104:107]
	v_mfma_f32_16x16x32_bf16 v[92:95], v[132:135], v[202:205], v[92:95]
	v_mfma_f32_16x16x32_bf16 v[88:91], v[156:159], v[202:205], v[88:91]
	v_mfma_f32_16x16x32_bf16 v[76:79], v[132:135], v[210:213], v[76:79]
	v_mfma_f32_16x16x32_bf16 v[72:75], v[156:159], v[210:213], v[72:75]
	s_setprio 0
	s_setprio 1
	v_mfma_f32_16x16x32_bf16 v[116:119], v[166:169], v[182:185], v[116:119]
	v_mfma_f32_16x16x32_bf16 v[112:115], v[174:177], v[182:185], v[112:115]
	v_mfma_f32_16x16x32_bf16 v[100:103], v[166:169], v[190:193], v[100:103]
	v_mfma_f32_16x16x32_bf16 v[96:99], v[174:177], v[190:193], v[96:99]
	v_mfma_f32_16x16x32_bf16 v[84:87], v[166:169], v[198:201], v[84:87]
	v_mfma_f32_16x16x32_bf16 v[80:83], v[174:177], v[198:201], v[80:83]
	v_mfma_f32_16x16x32_bf16 v[68:71], v[166:169], v[206:209], v[68:71]
	v_mfma_f32_16x16x32_bf16 v[64:67], v[174:177], v[206:209], v[64:67]
	v_mfma_f32_16x16x32_bf16 v[116:119], v[170:173], v[186:189], v[116:119]
	v_mfma_f32_16x16x32_bf16 v[112:115], v[178:181], v[186:189], v[112:115]
	v_mfma_f32_16x16x32_bf16 v[100:103], v[170:173], v[194:197], v[100:103]
	v_mfma_f32_16x16x32_bf16 v[96:99], v[178:181], v[194:197], v[96:99]
	v_mfma_f32_16x16x32_bf16 v[84:87], v[170:173], v[202:205], v[84:87]
	v_mfma_f32_16x16x32_bf16 v[80:83], v[178:181], v[202:205], v[80:83]
	v_mfma_f32_16x16x32_bf16 v[68:71], v[170:173], v[210:213], v[68:71]
	v_mfma_f32_16x16x32_bf16 v[64:67], v[178:181], v[210:213], v[64:67]
	s_setprio 0
	s_barrier
	s_add_i32 s53, s46, s39
	v_lshl_add_u64 v[160:161], s[28:29], 0, v[140:141]
	s_mov_b32 m0, s53
	ds_read_b128 v[182:185], v165 offset:16384
	ds_read_b128 v[186:189], v165 offset:17408
	ds_read_b128 v[190:193], v165 offset:18432
	ds_read_b128 v[194:197], v165 offset:19456
	ds_read_b128 v[198:201], v165 offset:20480
	ds_read_b128 v[202:205], v165 offset:21504
	ds_read_b128 v[206:209], v165 offset:22528
	ds_read_b128 v[210:213], v165 offset:23552
	global_load_lds_dwordx4 v[160:161], off
	s_add_i32 m0, s53, 0x2000
	s_add_u32 s54, s28, 0x100000
	v_lshl_add_u64 v[214:215], s[28:29], 0, v[136:137]
	s_addc_u32 s55, s29, 0
	s_add_i32 s53, s47, s39
	global_load_lds_dwordx4 v[214:215], off
	v_lshl_add_u64 v[216:217], s[54:55], 0, v[140:141]
	s_mov_b32 m0, s53
	v_lshl_add_u64 v[218:219], s[34:35], 0, v[138:139]
	global_load_lds_dwordx4 v[216:217], off
	v_lshl_add_u64 v[216:217], s[54:55], 0, v[136:137]
	s_add_i32 m0, s53, 0x2000
	s_nop 0
	global_load_lds_dwordx4 v[216:217], off
	v_lshl_add_u64 v[216:217], s[34:35], 0, v[142:143]
	s_mov_b32 m0, s8
	s_nop 0
	global_load_lds_dwordx4 v[216:217], off
	s_mov_b32 m0, s13
	s_nop 0
	global_load_lds_dwordx4 v[218:219], off
	s_cmp_lg_u32 s98, 0
	s_cbranch_scc1 .Lfi_p7_b
	s_waitcnt vmcnt(8)
; #define PG8_STAGE(bufoff, gbase, voff) do { _Pragma("unroll") for (int _i = 0; _i < 2; ++_i) \
;         __builtin_amdgcn_global_load_lds((const unsigned*)((const char*)(gbase) + (voff)[_i]), (PG8_LAS unsigned*)(lds + (bufoff) + ldsw + _i * 8192), 16, 0, 0); } while (0)
; #define PG8_LDA(dst, b, h) do { _Pragma("unroll") for (int m = 0; m < 4; ++m) _Pragma("unroll") for (int k = 0; k < 2; ++k) dst[m][k] = *(const PG8_LAS bf16x8*)(lds + PG8_SA(b, h) + aoff + m * 2048 + k * 1024); } while (0)
; #define PG8_LDB(dst, b, h) do { _Pragma("unroll") for (int n = 0; n < 2; ++n) _Pragma("unroll") for (int k = 0; k < 2; ++k) dst[n][k] = *(const PG8_LAS bf16x8*)(lds + PG8_SB(b, h) + boff + n * 2048 + k * 1024); } while (0)
; #define PG8_MMA(ai, bj, At, Bt) do { __builtin_amdgcn_s_setprio(1); _Pragma("unroll") for (int m = 0; m < 4; ++m) _Pragma("unroll") for (int n = 0; n < 2; ++n) _Pragma("unroll") for (int k = 0; k < 2; ++k) \
;         acc[ai][bj][m][n] = __builtin_amdgcn_mfma_f32_16x16x32_bf16(Bt[n][k], At[m][k], acc[ai][bj][m][n], 0, 0, 0); __builtin_amdgcn_s_setprio(0); } while (0)
; #define PG8_WAIT_V(n) asm volatile("s_waitcnt vmcnt(" #n ")" ::: "memory")
; #define PG8_WAIT_L(n) asm volatile("s_waitcnt lgkmcnt(" #n ")" ::: "memory")
; #define PG8_BAR __builtin_amdgcn_s_barrier()
; #define PG8_SCHED __builtin_amdgcn_sched_barrier(0)
;     ...
;             PG8_WAIT_V(8); PG8_WAIT_L(0); PG8_BAR; PG8_MMA(1, 0, At, B0); PG8_MMA(1, 1, At, B1); PG8_BAR; PG8_SCHED;
;             PG8_LDB(B0, 1, 0); PG8_LDB(B1, 1, 1); PG8_SCHED; PG8_LDA(At, 1, 0); PG8_STAGE(PG8_SA(0, 1), a2 + hstepA, voffA);
;             PG8_WAIT_V(8); PG8_WAIT_L(0); PG8_BAR; PG8_MMA(0, 0, At, B0); PG8_MMA(0, 1, At, B1); PG8_BAR; PG8_SCHED;
.Lfi_p7_bj:
	s_mov_b32 s98, 0
	s_waitcnt lgkmcnt(0)
	s_barrier
	s_setprio 1
	s_waitcnt lgkmcnt(0)
	v_mfma_f32_16x16x32_bf16 v[60:63], v[128:131], v[182:185], v[60:63]
	v_mfma_f32_16x16x32_bf16 v[56:59], v[152:155], v[182:185], v[56:59]
	v_mfma_f32_16x16x32_bf16 v[48:51], v[128:131], v[190:193], v[48:51]
	v_mfma_f32_16x16x32_bf16 v[40:43], v[152:155], v[190:193], v[40:43]
	v_mfma_f32_16x16x32_bf16 v[32:35], v[128:131], v[198:201], v[32:35]
	v_mfma_f32_16x16x32_bf16 v[24:27], v[152:155], v[198:201], v[24:27]
	v_mfma_f32_16x16x32_bf16 v[16:19], v[128:131], v[206:209], v[16:19]
	v_mfma_f32_16x16x32_bf16 v[8:11], v[152:155], v[206:209], v[8:11]
	v_mfma_f32_16x16x32_bf16 v[60:63], v[132:135], v[186:189], v[60:63]
	v_mfma_f32_16x16x32_bf16 v[56:59], v[156:159], v[186:189], v[56:59]
	v_mfma_f32_16x16x32_bf16 v[48:51], v[132:135], v[194:197], v[48:51]
	v_mfma_f32_16x16x32_bf16 v[40:43], v[156:159], v[194:197], v[40:43]
	v_mfma_f32_16x16x32_bf16 v[32:35], v[132:135], v[202:205], v[32:35]
	v_mfma_f32_16x16x32_bf16 v[24:27], v[156:159], v[202:205], v[24:27]
	v_mfma_f32_16x16x32_bf16 v[16:19], v[132:135], v[210:213], v[16:19]
	v_mfma_f32_16x16x32_bf16 v[8:11], v[156:159], v[210:213], v[8:11]
	s_setprio 0
	s_setprio 1
	v_mfma_f32_16x16x32_bf16 v[52:55], v[166:169], v[182:185], v[52:55]
	v_mfma_f32_16x16x32_bf16 v[44:47], v[174:177], v[182:185], v[44:47]
	v_mfma_f32_16x16x32_bf16 v[36:39], v[166:169], v[190:193], v[36:39]
	v_mfma_f32_16x16x32_bf16 v[28:31], v[174:177], v[190:193], v[28:31]
	v_mfma_f32_16x16x32_bf16 v[20:23], v[166:169], v[198:201], v[20:23]
	v_mfma_f32_16x16x32_bf16 v[12:15], v[174:177], v[198:201], v[12:15]
	v_mfma_f32_16x16x32_bf16 v[4:7], v[166:169], v[206:209], v[4:7]
	v_mfma_f32_16x16x32_bf16 v[0:3], v[174:177], v[206:209], v[0:3]
	v_mfma_f32_16x16x32_bf16 v[52:55], v[170:173], v[186:189], v[52:55]
	v_mfma_f32_16x16x32_bf16 v[44:47], v[178:181], v[186:189], v[44:47]
	v_mfma_f32_16x16x32_bf16 v[36:39], v[170:173], v[194:197], v[36:39]
	v_mfma_f32_16x16x32_bf16 v[28:31], v[178:181], v[194:197], v[28:31]
	v_mfma_f32_16x16x32_bf16 v[20:23], v[170:173], v[202:205], v[20:23]
	v_mfma_f32_16x16x32_bf16 v[12:15], v[178:181], v[202:205], v[12:15]
	v_mfma_f32_16x16x32_bf16 v[4:7], v[170:173], v[210:213], v[4:7]
	v_mfma_f32_16x16x32_bf16 v[0:3], v[178:181], v[210:213], v[0:3]
	s_setprio 0
	s_barrier
	s_add_i32 s53, 0, 0x18000
	s_add_i32 s54, 0, 0x1c000
	v_add_u32_e32 v156, s53, v162
	v_add_u32_e32 v178, s54, v162
	ds_read_b128 v[128:131], v156
	ds_read_b128 v[132:135], v156 offset:1024
	ds_read_b128 v[152:155], v156 offset:2048
	ds_read_b128 v[156:159], v156 offset:3072
	ds_read_b128 v[166:169], v178
	ds_read_b128 v[170:173], v178 offset:1024
	ds_read_b128 v[174:177], v178 offset:2048
	ds_read_b128 v[178:181], v178 offset:3072
	s_add_u32 s34, s34, 0x100000
	s_addc_u32 s35, s35, 0
	s_mov_b32 m0, s40
	v_lshl_add_u64 v[220:221], s[34:35], 0, v[142:143]
	ds_read_b128 v[182:185], v165 offset:32768
	ds_read_b128 v[186:189], v165 offset:33792
	ds_read_b128 v[190:193], v165 offset:34816
	ds_read_b128 v[194:197], v165 offset:35840
	ds_read_b128 v[198:201], v165 offset:36864
	ds_read_b128 v[202:205], v165 offset:37888
	ds_read_b128 v[206:209], v165 offset:38912
	ds_read_b128 v[210:213], v165 offset:39936
	global_load_lds_dwordx4 v[220:221], off
	v_lshl_add_u64 v[220:221], s[34:35], 0, v[138:139]
	s_mov_b32 m0, s41
	s_nop 0
	global_load_lds_dwordx4 v[220:221], off
	s_waitcnt vmcnt(8)
	s_waitcnt lgkmcnt(0)
	s_barrier
	s_setprio 1
	s_waitcnt lgkmcnt(0)
	v_mfma_f32_16x16x32_bf16 v[124:127], v[128:131], v[182:185], v[124:127]
	v_mfma_f32_16x16x32_bf16 v[120:123], v[152:155], v[182:185], v[120:123]
	v_mfma_f32_16x16x32_bf16 v[108:111], v[128:131], v[190:193], v[108:111]
	v_mfma_f32_16x16x32_bf16 v[104:107], v[152:155], v[190:193], v[104:107]
	v_mfma_f32_16x16x32_bf16 v[92:95], v[128:131], v[198:201], v[92:95]
	v_mfma_f32_16x16x32_bf16 v[88:91], v[152:155], v[198:201], v[88:91]
	v_mfma_f32_16x16x32_bf16 v[76:79], v[128:131], v[206:209], v[76:79]
	v_mfma_f32_16x16x32_bf16 v[72:75], v[152:155], v[206:209], v[72:75]
	v_mfma_f32_16x16x32_bf16 v[124:127], v[132:135], v[186:189], v[124:127]
	v_mfma_f32_16x16x32_bf16 v[120:123], v[156:159], v[186:189], v[120:123]
	v_mfma_f32_16x16x32_bf16 v[108:111], v[132:135], v[194:197], v[108:111]
	v_mfma_f32_16x16x32_bf16 v[104:107], v[156:159], v[194:197], v[104:107]
	v_mfma_f32_16x16x32_bf16 v[92:95], v[132:135], v[202:205], v[92:95]
	v_mfma_f32_16x16x32_bf16 v[88:91], v[156:159], v[202:205], v[88:91]
	v_mfma_f32_16x16x32_bf16 v[76:79], v[132:135], v[210:213], v[76:79]
	v_mfma_f32_16x16x32_bf16 v[72:75], v[156:159], v[210:213], v[72:75]
	s_setprio 0
	s_setprio 1
	v_mfma_f32_16x16x32_bf16 v[116:119], v[166:169], v[182:185], v[116:119]
	v_mfma_f32_16x16x32_bf16 v[112:115], v[174:177], v[182:185], v[112:115]
	v_mfma_f32_16x16x32_bf16 v[100:103], v[166:169], v[190:193], v[100:103]
	v_mfma_f32_16x16x32_bf16 v[96:99], v[174:177], v[190:193], v[96:99]
	v_mfma_f32_16x16x32_bf16 v[84:87], v[166:169], v[198:201], v[84:87]
	v_mfma_f32_16x16x32_bf16 v[80:83], v[174:177], v[198:201], v[80:83]
	v_mfma_f32_16x16x32_bf16 v[68:71], v[166:169], v[206:209], v[68:71]
	v_mfma_f32_16x16x32_bf16 v[64:67], v[174:177], v[206:209], v[64:67]
	v_mfma_f32_16x16x32_bf16 v[116:119], v[170:173], v[186:189], v[116:119]
	v_mfma_f32_16x16x32_bf16 v[112:115], v[178:181], v[186:189], v[112:115]
	v_mfma_f32_16x16x32_bf16 v[100:103], v[170:173], v[194:197], v[100:103]
	v_mfma_f32_16x16x32_bf16 v[96:99], v[178:181], v[194:197], v[96:99]
	v_mfma_f32_16x16x32_bf16 v[84:87], v[170:173], v[202:205], v[84:87]
	v_mfma_f32_16x16x32_bf16 v[80:83], v[178:181], v[202:205], v[80:83]
	v_mfma_f32_16x16x32_bf16 v[68:71], v[170:173], v[210:213], v[68:71]
	v_mfma_f32_16x16x32_bf16 v[64:67], v[178:181], v[210:213], v[64:67]
	s_setprio 0
	s_barrier
; #define PG8_STAGE(bufoff, gbase, voff) do { _Pragma("unroll") for (int _i = 0; _i < 2; ++_i) \
;         __builtin_amdgcn_global_load_lds((const unsigned*)((const char*)(gbase) + (voff)[_i]), (PG8_LAS unsigned*)(lds + (bufoff) + ldsw + _i * 8192), 16, 0, 0); } while (0)
; #define PG8_LDA(dst, b, h) do { _Pragma("unroll") for (int m = 0; m < 4; ++m) _Pragma("unroll") for (int k = 0; k < 2; ++k) dst[m][k] = *(const PG8_LAS bf16x8*)(lds + PG8_SA(b, h) + aoff + m * 2048 + k * 1024); } while (0)
; #define PG8_MMA(ai, bj, At, Bt) do { __builtin_amdgcn_s_setprio(1); _Pragma("unroll") for (int m = 0; m < 4; ++m) _Pragma("unroll") for (int n = 0; n < 2; ++n) _Pragma("unroll") for (int k = 0; k < 2; ++k) \
;         acc[ai][bj][m][n] = __builtin_amdgcn_mfma_f32_16x16x32_bf16(Bt[n][k], At[m][k], acc[ai][bj][m][n], 0, 0, 0); __builtin_amdgcn_s_setprio(0); } while (0)
; #define PG8_WAIT_V(n) asm volatile("s_waitcnt vmcnt(" #n ")" ::: "memory")
; #define PG8_WAIT_L(n) asm volatile("s_waitcnt lgkmcnt(" #n ")" ::: "memory")
; #define PG8_BAR __builtin_amdgcn_s_barrier()
; #define PG8_SCHED __builtin_amdgcn_sched_barrier(0)
;     ...
;         for (int t = 0; t < nt; t += 2) {
;     ...
;             PG8_LDA(At, 1, 1); PG8_STAGE(PG8_SB(1, 0), b3, voffB); PG8_STAGE(PG8_SB(1, 1), b3 + hstepB, voffB); PG8_STAGE(PG8_SA(1, 0), a3, voffA);
;             PG8_WAIT_V(8); PG8_WAIT_L(0); PG8_BAR; PG8_MMA(1, 0, At, B0); PG8_MMA(1, 1, At, B1); PG8_BAR; PG8_SCHED;
	s_add_i32 s34, s53, s39
	v_lshl_add_u64 v[160:161], v[160:161], 0, s[14:15]
	s_mov_b32 m0, s34
	ds_read_b128 v[182:185], v165 offset:49152
	ds_read_b128 v[186:189], v165 offset:50176
	ds_read_b128 v[190:193], v165 offset:51200
	ds_read_b128 v[194:197], v165 offset:52224
	ds_read_b128 v[198:201], v165 offset:53248
	ds_read_b128 v[202:205], v165 offset:54272
	ds_read_b128 v[206:209], v165 offset:55296
	ds_read_b128 v[210:213], v165 offset:56320
	global_load_lds_dwordx4 v[160:161], off
	s_add_i32 m0, s34, 0x2000
	s_add_u32 s28, s28, 0x100080
	v_lshl_add_u64 v[160:161], v[214:215], 0, s[14:15]
	s_addc_u32 s29, s29, 0
	s_add_i32 s34, s54, s39
	global_load_lds_dwordx4 v[160:161], off
	v_lshl_add_u64 v[160:161], s[28:29], 0, v[140:141]
	s_mov_b32 m0, s34
	s_nop 0
	global_load_lds_dwordx4 v[160:161], off
	v_lshl_add_u64 v[160:161], s[28:29], 0, v[136:137]
	s_add_i32 m0, s34, 0x2000
	s_nop 0
	global_load_lds_dwordx4 v[160:161], off
	v_lshl_add_u64 v[160:161], v[216:217], 0, s[14:15]
	s_mov_b32 m0, s44
	s_nop 0
	global_load_lds_dwordx4 v[160:161], off
	v_lshl_add_u64 v[160:161], v[218:219], 0, s[14:15]
	s_mov_b32 m0, s45
	s_nop 0
	global_load_lds_dwordx4 v[160:161], off
	s_waitcnt vmcnt(8)
	s_waitcnt lgkmcnt(0)
	s_barrier
	s_setprio 1
	s_waitcnt lgkmcnt(0)
	v_mfma_f32_16x16x32_bf16 v[60:63], v[128:131], v[182:185], v[60:63]
	v_mfma_f32_16x16x32_bf16 v[56:59], v[152:155], v[182:185], v[56:59]
	v_mfma_f32_16x16x32_bf16 v[48:51], v[128:131], v[190:193], v[48:51]
	v_mfma_f32_16x16x32_bf16 v[40:43], v[152:155], v[190:193], v[40:43]
	v_mfma_f32_16x16x32_bf16 v[32:35], v[128:131], v[198:201], v[32:35]
	v_mfma_f32_16x16x32_bf16 v[24:27], v[152:155], v[198:201], v[24:27]
	v_mfma_f32_16x16x32_bf16 v[16:19], v[128:131], v[206:209], v[16:19]
	v_mfma_f32_16x16x32_bf16 v[8:11], v[152:155], v[206:209], v[8:11]
	v_mfma_f32_16x16x32_bf16 v[60:63], v[132:135], v[186:189], v[60:63]
	v_mfma_f32_16x16x32_bf16 v[56:59], v[156:159], v[186:189], v[56:59]
	v_mfma_f32_16x16x32_bf16 v[48:51], v[132:135], v[194:197], v[48:51]
	v_mfma_f32_16x16x32_bf16 v[40:43], v[156:159], v[194:197], v[40:43]
	v_mfma_f32_16x16x32_bf16 v[32:35], v[132:135], v[202:205], v[32:35]
	v_mfma_f32_16x16x32_bf16 v[24:27], v[156:159], v[202:205], v[24:27]
	v_mfma_f32_16x16x32_bf16 v[16:19], v[132:135], v[210:213], v[16:19]
	v_mfma_f32_16x16x32_bf16 v[8:11], v[156:159], v[210:213], v[8:11]
	s_setprio 0
	s_setprio 1
	v_mfma_f32_16x16x32_bf16 v[52:55], v[166:169], v[182:185], v[52:55]
	v_mfma_f32_16x16x32_bf16 v[44:47], v[174:177], v[182:185], v[44:47]
	v_mfma_f32_16x16x32_bf16 v[36:39], v[166:169], v[190:193], v[36:39]
	v_mfma_f32_16x16x32_bf16 v[28:31], v[174:177], v[190:193], v[28:31]
	v_mfma_f32_16x16x32_bf16 v[20:23], v[166:169], v[198:201], v[20:23]
	v_mfma_f32_16x16x32_bf16 v[12:15], v[174:177], v[198:201], v[12:15]
	v_mfma_f32_16x16x32_bf16 v[4:7], v[166:169], v[206:209], v[4:7]
	v_mfma_f32_16x16x32_bf16 v[0:3], v[174:177], v[206:209], v[0:3]
	v_mfma_f32_16x16x32_bf16 v[52:55], v[170:173], v[186:189], v[52:55]
	v_mfma_f32_16x16x32_bf16 v[44:47], v[178:181], v[186:189], v[44:47]
	v_mfma_f32_16x16x32_bf16 v[36:39], v[170:173], v[194:197], v[36:39]
	v_mfma_f32_16x16x32_bf16 v[28:31], v[178:181], v[194:197], v[28:31]
	v_mfma_f32_16x16x32_bf16 v[20:23], v[170:173], v[202:205], v[20:23]
	v_mfma_f32_16x16x32_bf16 v[12:15], v[178:181], v[202:205], v[12:15]
	v_mfma_f32_16x16x32_bf16 v[4:7], v[170:173], v[210:213], v[4:7]
	v_mfma_f32_16x16x32_bf16 v[0:3], v[178:181], v[210:213], v[0:3]
	s_setprio 0
	s_barrier
	s_add_i32 s52, s52, 2
	s_add_u32 s26, s26, 0x100
	s_addc_u32 s27, s27, 0
	s_add_u32 s50, s50, 0x100
	s_addc_u32 s51, s51, 0
	s_cmp_gt_u32 s52, 61
	s_cbranch_scc0 .LBB0_1414
	s_mov_b32 s98, 1
	s_and_b64 vcc, exec, s[16:17]
	s_cbranch_vccz .LBB0_1417
	s_barrier
